# E20: K-loop counter/pointer increments moved into the shadow of the last block's trailing MFMAs (loop-edge edit), on top of E19
# speedup vs baseline: 1.0184x; 1.0015x over previous
.LBB0_225:
	ds_read_b128 v[128:131], v157
	ds_read_b128 v[132:135], v157 offset:1024
	ds_read_b128 v[146:149], v157 offset:2048
	ds_read_b128 v[164:167], v157 offset:3072
	ds_read_b128 v[168:171], v159
	ds_read_b128 v[172:175], v159 offset:1024
	ds_read_b128 v[176:179], v159 offset:2048
	ds_read_b128 v[180:183], v159 offset:3072
	s_add_u32 s36, s22, 0xfff80080
	s_addc_u32 s37, s23, -1
	s_cmp_eq_u32 s78, 28
	s_cselect_b32 s81, s5, s37
	s_cselect_b32 s80, s14, s36
	s_cselect_b32 vcc_hi, s20, s45
	s_cselect_b32 vcc_lo, s21, s24
	s_add_i32 m0, s77, 0xc000
	ds_read_b128 v[184:187], v161
	ds_read_b128 v[188:191], v161 offset:1024
	ds_read_b128 v[192:195], v161 offset:2048
	ds_read_b128 v[196:199], v161 offset:3072
	ds_read_b128 v[200:203], v161 offset:4096
	ds_read_b128 v[204:207], v161 offset:5120
	ds_read_b128 v[208:211], v161 offset:6144
	ds_read_b128 v[212:215], v161 offset:7168
	global_load_lds_dwordx4 v140, s[22:23]
	s_add_i32 m0, s77, 0xe000
	s_nop 0
	s_add_u32 s98, s22, s6
	s_addc_u32 s99, s23, s7
	global_load_lds_dwordx4 v140, s[98:99]
	s_waitcnt vmcnt(8)
	s_waitcnt lgkmcnt(0)
	s_barrier
	s_setprio 1
	s_waitcnt lgkmcnt(0)
	v_mfma_i32_16x16x64_i8 v[0:3], v[128:131], v[184:187], v[0:3]
	v_mfma_i32_16x16x64_i8 v[0:3], v[132:135], v[188:191], v[0:3]
	v_mfma_i32_16x16x64_i8 v[56:59], v[146:149], v[184:187], v[56:59]
	v_mfma_i32_16x16x64_i8 v[56:59], v[164:167], v[188:191], v[56:59]
	v_mfma_i32_16x16x64_i8 v[4:7], v[128:131], v[192:195], v[4:7]
	v_mfma_i32_16x16x64_i8 v[4:7], v[132:135], v[196:199], v[4:7]
	v_mfma_i32_16x16x64_i8 v[52:55], v[146:149], v[192:195], v[52:55]
	v_mfma_i32_16x16x64_i8 v[52:55], v[164:167], v[196:199], v[52:55]
	v_mfma_i32_16x16x64_i8 v[12:15], v[128:131], v[200:203], v[12:15]
	v_mfma_i32_16x16x64_i8 v[12:15], v[132:135], v[204:207], v[12:15]
	v_mfma_i32_16x16x64_i8 v[48:51], v[146:149], v[200:203], v[48:51]
	v_mfma_i32_16x16x64_i8 v[48:51], v[164:167], v[204:207], v[48:51]
	v_mfma_i32_16x16x64_i8 v[8:11], v[128:131], v[208:211], v[8:11]
	v_mfma_i32_16x16x64_i8 v[8:11], v[132:135], v[212:215], v[8:11]
	v_mfma_i32_16x16x64_i8 v[44:47], v[146:149], v[208:211], v[44:47]
	v_mfma_i32_16x16x64_i8 v[44:47], v[164:167], v[212:215], v[44:47]
	s_setprio 0
	s_setprio 1
	v_mfma_i32_16x16x64_i8 v[88:91], v[168:171], v[184:187], v[88:91]
	v_mfma_i32_16x16x64_i8 v[88:91], v[172:175], v[188:191], v[88:91]
	v_mfma_i32_16x16x64_i8 v[120:123], v[176:179], v[184:187], v[120:123]
	v_mfma_i32_16x16x64_i8 v[120:123], v[180:183], v[188:191], v[120:123]
	v_mfma_i32_16x16x64_i8 v[84:87], v[168:171], v[192:195], v[84:87]
	v_mfma_i32_16x16x64_i8 v[84:87], v[172:175], v[196:199], v[84:87]
	v_mfma_i32_16x16x64_i8 v[116:119], v[176:179], v[192:195], v[116:119]
	v_mfma_i32_16x16x64_i8 v[116:119], v[180:183], v[196:199], v[116:119]
	v_mfma_i32_16x16x64_i8 v[80:83], v[168:171], v[200:203], v[80:83]
	v_mfma_i32_16x16x64_i8 v[80:83], v[172:175], v[204:207], v[80:83]
	v_mfma_i32_16x16x64_i8 v[112:115], v[176:179], v[200:203], v[112:115]
	v_mfma_i32_16x16x64_i8 v[112:115], v[180:183], v[204:207], v[112:115]
	s_setprio 2
	s_barrier
	v_mfma_i32_16x16x64_i8 v[76:79], v[168:171], v[208:211], v[76:79]
	ds_read_b128 v[184:187], v161 offset:16384
	ds_read_b128 v[188:191], v161 offset:17408
	v_mfma_i32_16x16x64_i8 v[76:79], v[172:175], v[212:215], v[76:79]
	ds_read_b128 v[192:195], v161 offset:18432
	ds_read_b128 v[196:199], v161 offset:19456
	v_mfma_i32_16x16x64_i8 v[108:111], v[176:179], v[208:211], v[108:111]
	ds_read_b128 v[200:203], v161 offset:20480
	ds_read_b128 v[204:207], v161 offset:21504
	v_mfma_i32_16x16x64_i8 v[108:111], v[180:183], v[212:215], v[108:111]
	s_setprio 0
	s_add_i32 s36, s86, s63
	s_mov_b32 m0, s36
	ds_read_b128 v[208:211], v161 offset:22528
	ds_read_b128 v[212:215], v161 offset:23552
	global_load_lds_dwordx4 v138, vcc
	s_add_i32 m0, s36, 0x2000
	s_add_i32 s36, s87, s63
	s_add_u32 s98, vcc_lo, s6
	s_addc_u32 s99, vcc_hi, s7
	global_load_lds_dwordx4 v138, s[98:99]
	s_mov_b32 m0, s36
	s_nop 0
	s_add_u32 s98, vcc_lo, s8
	s_addc_u32 s99, vcc_hi, s9
	global_load_lds_dwordx4 v138, s[98:99]
	s_add_i32 m0, s36, 0x2000
	s_nop 0
	s_add_u32 s98, vcc_lo, s10
	s_addc_u32 s99, vcc_hi, s11
	global_load_lds_dwordx4 v138, s[98:99]
	s_mov_b32 m0, s77
	s_nop 0
	global_load_lds_dwordx4 v136, s[80:81]
	s_mov_b32 m0, s97
	s_nop 0
	s_add_u32 s98, s80, s6
	s_addc_u32 s99, s81, s7
	global_load_lds_dwordx4 v136, s[98:99]
	s_waitcnt vmcnt(8)
	s_waitcnt lgkmcnt(0)
	s_barrier
	s_setprio 1
	s_waitcnt lgkmcnt(0)
	v_mfma_i32_16x16x64_i8 v[20:23], v[128:131], v[184:187], v[20:23]
	v_mfma_i32_16x16x64_i8 v[20:23], v[132:135], v[188:191], v[20:23]
	v_mfma_i32_16x16x64_i8 v[40:43], v[146:149], v[184:187], v[40:43]
	v_mfma_i32_16x16x64_i8 v[40:43], v[164:167], v[188:191], v[40:43]
	v_mfma_i32_16x16x64_i8 v[16:19], v[128:131], v[192:195], v[16:19]
	v_mfma_i32_16x16x64_i8 v[16:19], v[132:135], v[196:199], v[16:19]
	v_mfma_i32_16x16x64_i8 v[36:39], v[146:149], v[192:195], v[36:39]
	v_mfma_i32_16x16x64_i8 v[36:39], v[164:167], v[196:199], v[36:39]
	v_mfma_i32_16x16x64_i8 v[24:27], v[128:131], v[200:203], v[24:27]
	v_mfma_i32_16x16x64_i8 v[24:27], v[132:135], v[204:207], v[24:27]
	v_mfma_i32_16x16x64_i8 v[32:35], v[146:149], v[200:203], v[32:35]
	v_mfma_i32_16x16x64_i8 v[32:35], v[164:167], v[204:207], v[32:35]
	v_mfma_i32_16x16x64_i8 v[28:31], v[128:131], v[208:211], v[28:31]
	v_mfma_i32_16x16x64_i8 v[28:31], v[132:135], v[212:215], v[28:31]
	v_mfma_i32_16x16x64_i8 v[60:63], v[146:149], v[208:211], v[60:63]
	v_mfma_i32_16x16x64_i8 v[60:63], v[164:167], v[212:215], v[60:63]
	s_setprio 0
	s_setprio 1
	v_mfma_i32_16x16x64_i8 v[72:75], v[168:171], v[184:187], v[72:75]
	v_mfma_i32_16x16x64_i8 v[72:75], v[172:175], v[188:191], v[72:75]
	v_mfma_i32_16x16x64_i8 v[104:107], v[176:179], v[184:187], v[104:107]
	v_mfma_i32_16x16x64_i8 v[104:107], v[180:183], v[188:191], v[104:107]
	v_mfma_i32_16x16x64_i8 v[68:71], v[168:171], v[192:195], v[68:71]
	v_mfma_i32_16x16x64_i8 v[68:71], v[172:175], v[196:199], v[68:71]
	v_mfma_i32_16x16x64_i8 v[100:103], v[176:179], v[192:195], v[100:103]
	v_mfma_i32_16x16x64_i8 v[100:103], v[180:183], v[196:199], v[100:103]
	v_mfma_i32_16x16x64_i8 v[64:67], v[168:171], v[200:203], v[64:67]
	v_mfma_i32_16x16x64_i8 v[64:67], v[172:175], v[204:207], v[64:67]
	v_mfma_i32_16x16x64_i8 v[96:99], v[176:179], v[200:203], v[96:99]
	v_mfma_i32_16x16x64_i8 v[96:99], v[180:183], v[204:207], v[96:99]
	s_setprio 2
	s_barrier
	v_mfma_i32_16x16x64_i8 v[92:95], v[168:171], v[208:211], v[92:95]
	ds_read_b128 v[184:187], v161 offset:32768
	ds_read_b128 v[188:191], v161 offset:33792
	v_mfma_i32_16x16x64_i8 v[92:95], v[172:175], v[212:215], v[92:95]
	ds_read_b128 v[192:195], v161 offset:34816
	ds_read_b128 v[196:199], v161 offset:35840
	v_mfma_i32_16x16x64_i8 v[124:127], v[176:179], v[208:211], v[124:127]
	ds_read_b128 v[200:203], v161 offset:36864
	ds_read_b128 v[204:207], v161 offset:37888
	v_mfma_i32_16x16x64_i8 v[124:127], v[180:183], v[212:215], v[124:127]
	s_setprio 0
	s_add_i32 s36, 0, 0x18000
	v_add_u32_e32 v152, s36, v153
	s_add_i32 s37, 0, 0x1c000
	ds_read_b128 v[128:131], v152
	ds_read_b128 v[132:135], v152 offset:1024
	ds_read_b128 v[146:149], v152 offset:2048
	ds_read_b128 v[164:167], v152 offset:3072
	v_add_u32_e32 v152, s37, v153
	ds_read_b128 v[168:171], v152
	ds_read_b128 v[172:175], v152 offset:1024
	ds_read_b128 v[176:179], v152 offset:2048
	ds_read_b128 v[180:183], v152 offset:3072
	s_mov_b32 m0, s33
	ds_read_b128 v[208:211], v161 offset:38912
	ds_read_b128 v[212:215], v161 offset:39936
	s_add_u32 s98, s80, s8
	s_addc_u32 s99, s81, s9
	global_load_lds_dwordx4 v136, s[98:99]
	s_mov_b32 m0, s93
	s_nop 0
	s_add_u32 s98, s80, s10
	s_addc_u32 s99, s81, s11
	global_load_lds_dwordx4 v136, s[98:99]
	s_waitcnt vmcnt(8)
	s_waitcnt lgkmcnt(0)
	s_barrier
	s_setprio 1
	s_waitcnt lgkmcnt(0)
	v_mfma_i32_16x16x64_i8 v[0:3], v[128:131], v[184:187], v[0:3]
	v_mfma_i32_16x16x64_i8 v[0:3], v[132:135], v[188:191], v[0:3]
	v_mfma_i32_16x16x64_i8 v[56:59], v[146:149], v[184:187], v[56:59]
	v_mfma_i32_16x16x64_i8 v[56:59], v[164:167], v[188:191], v[56:59]
	v_mfma_i32_16x16x64_i8 v[4:7], v[128:131], v[192:195], v[4:7]
	v_mfma_i32_16x16x64_i8 v[4:7], v[132:135], v[196:199], v[4:7]
	v_mfma_i32_16x16x64_i8 v[52:55], v[146:149], v[192:195], v[52:55]
	v_mfma_i32_16x16x64_i8 v[52:55], v[164:167], v[196:199], v[52:55]
	v_mfma_i32_16x16x64_i8 v[12:15], v[128:131], v[200:203], v[12:15]
	v_mfma_i32_16x16x64_i8 v[12:15], v[132:135], v[204:207], v[12:15]
	v_mfma_i32_16x16x64_i8 v[48:51], v[146:149], v[200:203], v[48:51]
	v_mfma_i32_16x16x64_i8 v[48:51], v[164:167], v[204:207], v[48:51]
	v_mfma_i32_16x16x64_i8 v[8:11], v[128:131], v[208:211], v[8:11]
	v_mfma_i32_16x16x64_i8 v[8:11], v[132:135], v[212:215], v[8:11]
	v_mfma_i32_16x16x64_i8 v[44:47], v[146:149], v[208:211], v[44:47]
	v_mfma_i32_16x16x64_i8 v[44:47], v[164:167], v[212:215], v[44:47]
	s_setprio 0
	s_setprio 1
	v_mfma_i32_16x16x64_i8 v[88:91], v[168:171], v[184:187], v[88:91]
	v_mfma_i32_16x16x64_i8 v[88:91], v[172:175], v[188:191], v[88:91]
	v_mfma_i32_16x16x64_i8 v[120:123], v[176:179], v[184:187], v[120:123]
	v_mfma_i32_16x16x64_i8 v[120:123], v[180:183], v[188:191], v[120:123]
	v_mfma_i32_16x16x64_i8 v[84:87], v[168:171], v[192:195], v[84:87]
	v_mfma_i32_16x16x64_i8 v[84:87], v[172:175], v[196:199], v[84:87]
	v_mfma_i32_16x16x64_i8 v[116:119], v[176:179], v[192:195], v[116:119]
	v_mfma_i32_16x16x64_i8 v[116:119], v[180:183], v[196:199], v[116:119]
	v_mfma_i32_16x16x64_i8 v[80:83], v[168:171], v[200:203], v[80:83]
	v_mfma_i32_16x16x64_i8 v[80:83], v[172:175], v[204:207], v[80:83]
	v_mfma_i32_16x16x64_i8 v[112:115], v[176:179], v[200:203], v[112:115]
	v_mfma_i32_16x16x64_i8 v[112:115], v[180:183], v[204:207], v[112:115]
	s_setprio 2
	s_barrier
	v_mfma_i32_16x16x64_i8 v[76:79], v[168:171], v[208:211], v[76:79]
	ds_read_b128 v[184:187], v161 offset:49152
	ds_read_b128 v[188:191], v161 offset:50176
	v_mfma_i32_16x16x64_i8 v[76:79], v[172:175], v[212:215], v[76:79]
	ds_read_b128 v[192:195], v161 offset:51200
	ds_read_b128 v[196:199], v161 offset:52224
	v_mfma_i32_16x16x64_i8 v[108:111], v[176:179], v[208:211], v[108:111]
	ds_read_b128 v[200:203], v161 offset:53248
	ds_read_b128 v[204:207], v161 offset:54272
	v_mfma_i32_16x16x64_i8 v[108:111], v[180:183], v[212:215], v[108:111]
	s_setprio 0
	s_add_i32 s36, s36, s63
	s_mov_b32 m0, s36
	ds_read_b128 v[208:211], v161 offset:55296
	ds_read_b128 v[212:215], v161 offset:56320
	s_add_u32 s98, vcc_lo, s46
	s_addc_u32 s99, vcc_hi, s47
	global_load_lds_dwordx4 v138, s[98:99]
	s_add_i32 m0, s36, 0x2000
	s_add_i32 s36, s37, s63
	s_add_u32 s98, vcc_lo, s48
	s_addc_u32 s99, vcc_hi, s49
	global_load_lds_dwordx4 v138, s[98:99]
	s_mov_b32 m0, s36
	s_add_u32 s98, vcc_lo, s54
	s_addc_u32 s99, vcc_hi, s55
	global_load_lds_dwordx4 v138, s[98:99]
	s_add_i32 m0, s36, 0x2000
	s_nop 0
	s_add_u32 s98, vcc_lo, s56
	s_addc_u32 s99, vcc_hi, s57
	global_load_lds_dwordx4 v138, s[98:99]
	s_mov_b32 m0, s95
	s_nop 0
	s_add_u32 s98, s80, s46
	s_addc_u32 s99, s81, s47
	global_load_lds_dwordx4 v136, s[98:99]
	s_mov_b32 m0, s82
	s_nop 0
	s_add_u32 s98, s80, s48
	s_addc_u32 s99, s81, s49
	global_load_lds_dwordx4 v136, s[98:99]
	s_waitcnt vmcnt(8)
	s_waitcnt lgkmcnt(0)
	s_barrier
	s_setprio 1
	s_waitcnt lgkmcnt(0)
	v_mfma_i32_16x16x64_i8 v[20:23], v[128:131], v[184:187], v[20:23]
	v_mfma_i32_16x16x64_i8 v[20:23], v[132:135], v[188:191], v[20:23]
	v_mfma_i32_16x16x64_i8 v[40:43], v[146:149], v[184:187], v[40:43]
	v_mfma_i32_16x16x64_i8 v[40:43], v[164:167], v[188:191], v[40:43]
	v_mfma_i32_16x16x64_i8 v[16:19], v[128:131], v[192:195], v[16:19]
	v_mfma_i32_16x16x64_i8 v[16:19], v[132:135], v[196:199], v[16:19]
	v_mfma_i32_16x16x64_i8 v[36:39], v[146:149], v[192:195], v[36:39]
	v_mfma_i32_16x16x64_i8 v[36:39], v[164:167], v[196:199], v[36:39]
	v_mfma_i32_16x16x64_i8 v[24:27], v[128:131], v[200:203], v[24:27]
	v_mfma_i32_16x16x64_i8 v[24:27], v[132:135], v[204:207], v[24:27]
	v_mfma_i32_16x16x64_i8 v[32:35], v[146:149], v[200:203], v[32:35]
	v_mfma_i32_16x16x64_i8 v[32:35], v[164:167], v[204:207], v[32:35]
	v_mfma_i32_16x16x64_i8 v[28:31], v[128:131], v[208:211], v[28:31]
	v_mfma_i32_16x16x64_i8 v[28:31], v[132:135], v[212:215], v[28:31]
	v_mfma_i32_16x16x64_i8 v[60:63], v[146:149], v[208:211], v[60:63]
	v_mfma_i32_16x16x64_i8 v[60:63], v[164:167], v[212:215], v[60:63]
	s_setprio 0
	s_setprio 1
	v_mfma_i32_16x16x64_i8 v[72:75], v[168:171], v[184:187], v[72:75]
	v_mfma_i32_16x16x64_i8 v[72:75], v[172:175], v[188:191], v[72:75]
	v_mfma_i32_16x16x64_i8 v[104:107], v[176:179], v[184:187], v[104:107]
	v_mfma_i32_16x16x64_i8 v[104:107], v[180:183], v[188:191], v[104:107]
	v_mfma_i32_16x16x64_i8 v[68:71], v[168:171], v[192:195], v[68:71]
	v_mfma_i32_16x16x64_i8 v[68:71], v[172:175], v[196:199], v[68:71]
	v_mfma_i32_16x16x64_i8 v[100:103], v[176:179], v[192:195], v[100:103]
	v_mfma_i32_16x16x64_i8 v[100:103], v[180:183], v[196:199], v[100:103]
	v_mfma_i32_16x16x64_i8 v[64:67], v[168:171], v[200:203], v[64:67]
	v_mfma_i32_16x16x64_i8 v[64:67], v[172:175], v[204:207], v[64:67]
	v_mfma_i32_16x16x64_i8 v[96:99], v[176:179], v[200:203], v[96:99]
	v_mfma_i32_16x16x64_i8 v[96:99], v[180:183], v[204:207], v[96:99]
	s_setprio 2
	s_barrier
	v_mfma_i32_16x16x64_i8 v[92:95], v[168:171], v[208:211], v[92:95]
	s_add_i32 s78, s78, 2
	s_add_u32 s24, s24, 0x100
	s_addc_u32 s45, s45, 0
	v_mfma_i32_16x16x64_i8 v[92:95], v[172:175], v[212:215], v[92:95]
	s_add_u32 s22, s22, 0x100
	s_addc_u32 s23, s23, 0
	v_mfma_i32_16x16x64_i8 v[124:127], v[176:179], v[208:211], v[124:127]
	v_mfma_i32_16x16x64_i8 v[124:127], v[180:183], v[212:215], v[124:127]
	s_setprio 0
	s_cmp_gt_u32 s78, 29
	s_cbranch_scc0 .LBB0_225
	v_readlane_b32 s14, v250, 9
	v_readlane_b32 s15, v250, 10
	s_and_b64 vcc, exec, s[14:15]
	s_cbranch_vccz .LBB0_228
	s_barrier

.LBB0_298:
	ds_read_b128 v[128:131], v153
	ds_read_b128 v[132:135], v153 offset:1024
	ds_read_b128 v[146:149], v153 offset:2048
	ds_read_b128 v[158:161], v153 offset:3072
	ds_read_b128 v[162:165], v154
	ds_read_b128 v[166:169], v154 offset:1024
	ds_read_b128 v[170:173], v154 offset:2048
	ds_read_b128 v[174:177], v154 offset:3072
	s_add_u32 s36, s78, 0xfff00080
	s_addc_u32 s37, s79, -1
	s_cmp_eq_u32 s81, 60
	s_cselect_b32 s97, s5, s37
	s_cselect_b32 s96, s14, s36
	s_cselect_b32 vcc_hi, s20, s80
	s_cselect_b32 vcc_lo, s21, s22
	s_add_i32 m0, s33, 0xc000
	ds_read_b128 v[178:181], v155
	ds_read_b128 v[182:185], v155 offset:1024
	ds_read_b128 v[186:189], v155 offset:2048
	ds_read_b128 v[190:193], v155 offset:3072
	ds_read_b128 v[194:197], v155 offset:4096
	ds_read_b128 v[198:201], v155 offset:5120
	ds_read_b128 v[202:205], v155 offset:6144
	ds_read_b128 v[206:209], v155 offset:7168
	global_load_lds_dwordx4 v140, s[78:79]
	s_add_i32 m0, s33, 0xe000
	s_nop 0
	s_add_u32 s98, s78, s0
	s_addc_u32 s99, s79, s1
	global_load_lds_dwordx4 v140, s[98:99]
	s_waitcnt vmcnt(8)
	s_waitcnt lgkmcnt(0)
	s_barrier
	s_setprio 1
	s_waitcnt lgkmcnt(0)
	v_mfma_f32_16x16x32_bf16 v[124:127], v[128:131], v[178:181], v[124:127]
	v_mfma_f32_16x16x32_bf16 v[124:127], v[132:135], v[182:185], v[124:127]
	v_mfma_f32_16x16x32_bf16 v[120:123], v[146:149], v[178:181], v[120:123]
	v_mfma_f32_16x16x32_bf16 v[120:123], v[158:161], v[182:185], v[120:123]
	v_mfma_f32_16x16x32_bf16 v[112:115], v[128:131], v[186:189], v[112:115]
	v_mfma_f32_16x16x32_bf16 v[112:115], v[132:135], v[190:193], v[112:115]
	v_mfma_f32_16x16x32_bf16 v[108:111], v[146:149], v[186:189], v[108:111]
	v_mfma_f32_16x16x32_bf16 v[108:111], v[158:161], v[190:193], v[108:111]
	v_mfma_f32_16x16x32_bf16 v[100:103], v[128:131], v[194:197], v[100:103]
	v_mfma_f32_16x16x32_bf16 v[100:103], v[132:135], v[198:201], v[100:103]
	v_mfma_f32_16x16x32_bf16 v[92:95], v[146:149], v[194:197], v[92:95]
	v_mfma_f32_16x16x32_bf16 v[92:95], v[158:161], v[198:201], v[92:95]
	v_mfma_f32_16x16x32_bf16 v[84:87], v[128:131], v[202:205], v[84:87]
	v_mfma_f32_16x16x32_bf16 v[84:87], v[132:135], v[206:209], v[84:87]
	v_mfma_f32_16x16x32_bf16 v[76:79], v[146:149], v[202:205], v[76:79]
	v_mfma_f32_16x16x32_bf16 v[76:79], v[158:161], v[206:209], v[76:79]
	s_setprio 0
	s_setprio 1
	v_mfma_f32_16x16x32_bf16 v[116:119], v[162:165], v[178:181], v[116:119]
	v_mfma_f32_16x16x32_bf16 v[116:119], v[166:169], v[182:185], v[116:119]
	v_mfma_f32_16x16x32_bf16 v[104:107], v[170:173], v[178:181], v[104:107]
	v_mfma_f32_16x16x32_bf16 v[104:107], v[174:177], v[182:185], v[104:107]
	v_mfma_f32_16x16x32_bf16 v[96:99], v[162:165], v[186:189], v[96:99]
	v_mfma_f32_16x16x32_bf16 v[96:99], v[166:169], v[190:193], v[96:99]
	v_mfma_f32_16x16x32_bf16 v[88:91], v[170:173], v[186:189], v[88:91]
	v_mfma_f32_16x16x32_bf16 v[88:91], v[174:177], v[190:193], v[88:91]
	v_mfma_f32_16x16x32_bf16 v[80:83], v[162:165], v[194:197], v[80:83]
	v_mfma_f32_16x16x32_bf16 v[80:83], v[166:169], v[198:201], v[80:83]
	v_mfma_f32_16x16x32_bf16 v[72:75], v[170:173], v[194:197], v[72:75]
	v_mfma_f32_16x16x32_bf16 v[72:75], v[174:177], v[198:201], v[72:75]
	s_setprio 2
	s_barrier
	v_mfma_f32_16x16x32_bf16 v[68:71], v[162:165], v[202:205], v[68:71]
	ds_read_b128 v[178:181], v155 offset:16384
	ds_read_b128 v[182:185], v155 offset:17408
	v_mfma_f32_16x16x32_bf16 v[68:71], v[166:169], v[206:209], v[68:71]
	ds_read_b128 v[186:189], v155 offset:18432
	ds_read_b128 v[190:193], v155 offset:19456
	v_mfma_f32_16x16x32_bf16 v[64:67], v[170:173], v[202:205], v[64:67]
	ds_read_b128 v[194:197], v155 offset:20480
	ds_read_b128 v[198:201], v155 offset:21504
	v_mfma_f32_16x16x32_bf16 v[64:67], v[174:177], v[206:209], v[64:67]
	s_setprio 0
	s_add_i32 s36, s82, s63
	s_mov_b32 m0, s36
	ds_read_b128 v[202:205], v155 offset:22528
	ds_read_b128 v[206:209], v155 offset:23552
	global_load_lds_dwordx4 v138, vcc
	s_add_i32 m0, s36, 0x2000
	s_add_i32 s36, s83, s63
	s_add_u32 s98, vcc_lo, s0
	s_addc_u32 s99, vcc_hi, s1
	global_load_lds_dwordx4 v138, s[98:99]
	s_mov_b32 m0, s36
	s_nop 0
	s_add_u32 s98, vcc_lo, s6
	s_addc_u32 s99, vcc_hi, s7
	global_load_lds_dwordx4 v138, s[98:99]
	s_add_i32 m0, s36, 0x2000
	s_nop 0
	s_add_u32 s98, vcc_lo, s8
	s_addc_u32 s99, vcc_hi, s9
	global_load_lds_dwordx4 v138, s[98:99]
	s_mov_b32 m0, s33
	s_nop 0
	global_load_lds_dwordx4 v136, s[96:97]
	s_mov_b32 m0, s55
	s_nop 0
	s_add_u32 s98, s96, s0
	s_addc_u32 s99, s97, s1
	global_load_lds_dwordx4 v136, s[98:99]
	s_waitcnt vmcnt(8)
	s_waitcnt lgkmcnt(0)
	s_barrier
	s_setprio 1
	s_waitcnt lgkmcnt(0)
	v_mfma_f32_16x16x32_bf16 v[60:63], v[128:131], v[178:181], v[60:63]
	v_mfma_f32_16x16x32_bf16 v[60:63], v[132:135], v[182:185], v[60:63]
	v_mfma_f32_16x16x32_bf16 v[56:59], v[146:149], v[178:181], v[56:59]
	v_mfma_f32_16x16x32_bf16 v[56:59], v[158:161], v[182:185], v[56:59]
	v_mfma_f32_16x16x32_bf16 v[52:55], v[128:131], v[186:189], v[52:55]
	v_mfma_f32_16x16x32_bf16 v[52:55], v[132:135], v[190:193], v[52:55]
	v_mfma_f32_16x16x32_bf16 v[44:47], v[146:149], v[186:189], v[44:47]
	v_mfma_f32_16x16x32_bf16 v[44:47], v[158:161], v[190:193], v[44:47]
	v_mfma_f32_16x16x32_bf16 v[36:39], v[128:131], v[194:197], v[36:39]
	v_mfma_f32_16x16x32_bf16 v[36:39], v[132:135], v[198:201], v[36:39]
	v_mfma_f32_16x16x32_bf16 v[28:31], v[146:149], v[194:197], v[28:31]
	v_mfma_f32_16x16x32_bf16 v[28:31], v[158:161], v[198:201], v[28:31]
	v_mfma_f32_16x16x32_bf16 v[20:23], v[128:131], v[202:205], v[20:23]
	v_mfma_f32_16x16x32_bf16 v[20:23], v[132:135], v[206:209], v[20:23]
	v_mfma_f32_16x16x32_bf16 v[12:15], v[146:149], v[202:205], v[12:15]
	v_mfma_f32_16x16x32_bf16 v[12:15], v[158:161], v[206:209], v[12:15]
	s_setprio 0
	s_setprio 1
	v_mfma_f32_16x16x32_bf16 v[48:51], v[162:165], v[178:181], v[48:51]
	v_mfma_f32_16x16x32_bf16 v[48:51], v[166:169], v[182:185], v[48:51]
	v_mfma_f32_16x16x32_bf16 v[40:43], v[170:173], v[178:181], v[40:43]
	v_mfma_f32_16x16x32_bf16 v[40:43], v[174:177], v[182:185], v[40:43]
	v_mfma_f32_16x16x32_bf16 v[32:35], v[162:165], v[186:189], v[32:35]
	v_mfma_f32_16x16x32_bf16 v[32:35], v[166:169], v[190:193], v[32:35]
	v_mfma_f32_16x16x32_bf16 v[24:27], v[170:173], v[186:189], v[24:27]
	v_mfma_f32_16x16x32_bf16 v[24:27], v[174:177], v[190:193], v[24:27]
	v_mfma_f32_16x16x32_bf16 v[16:19], v[162:165], v[194:197], v[16:19]
	v_mfma_f32_16x16x32_bf16 v[16:19], v[166:169], v[198:201], v[16:19]
	v_mfma_f32_16x16x32_bf16 v[8:11], v[170:173], v[194:197], v[8:11]
	v_mfma_f32_16x16x32_bf16 v[8:11], v[174:177], v[198:201], v[8:11]
	s_setprio 2
	s_barrier
	v_mfma_f32_16x16x32_bf16 v[4:7], v[162:165], v[202:205], v[4:7]
	ds_read_b128 v[178:181], v155 offset:32768
	ds_read_b128 v[182:185], v155 offset:33792
	v_mfma_f32_16x16x32_bf16 v[4:7], v[166:169], v[206:209], v[4:7]
	ds_read_b128 v[186:189], v155 offset:34816
	ds_read_b128 v[190:193], v155 offset:35840
	v_mfma_f32_16x16x32_bf16 v[0:3], v[170:173], v[202:205], v[0:3]
	ds_read_b128 v[194:197], v155 offset:36864
	ds_read_b128 v[198:201], v155 offset:37888
	v_mfma_f32_16x16x32_bf16 v[0:3], v[174:177], v[206:209], v[0:3]
	s_setprio 0
	s_add_i32 s36, 0, 0x18000
	v_add_u32_e32 v157, s36, v152
	s_add_i32 s37, 0, 0x1c000
	ds_read_b128 v[128:131], v157
	ds_read_b128 v[132:135], v157 offset:1024
	ds_read_b128 v[146:149], v157 offset:2048
	ds_read_b128 v[158:161], v157 offset:3072
	v_add_u32_e32 v157, s37, v152
	ds_read_b128 v[162:165], v157
	ds_read_b128 v[166:169], v157 offset:1024
	ds_read_b128 v[170:173], v157 offset:2048
	ds_read_b128 v[174:177], v157 offset:3072
	s_mov_b32 m0, s57
	ds_read_b128 v[202:205], v155 offset:38912
	ds_read_b128 v[206:209], v155 offset:39936
	s_add_u32 s98, s96, s6
	s_addc_u32 s99, s97, s7
	global_load_lds_dwordx4 v136, s[98:99]
	s_mov_b32 m0, s59
	s_nop 0
	s_add_u32 s98, s96, s8
	s_addc_u32 s99, s97, s9
	global_load_lds_dwordx4 v136, s[98:99]
	s_waitcnt vmcnt(8)
	s_waitcnt lgkmcnt(0)
	s_barrier
	s_setprio 1
	s_waitcnt lgkmcnt(0)
	v_mfma_f32_16x16x32_bf16 v[124:127], v[128:131], v[178:181], v[124:127]
	v_mfma_f32_16x16x32_bf16 v[124:127], v[132:135], v[182:185], v[124:127]
	v_mfma_f32_16x16x32_bf16 v[120:123], v[146:149], v[178:181], v[120:123]
	v_mfma_f32_16x16x32_bf16 v[120:123], v[158:161], v[182:185], v[120:123]
	v_mfma_f32_16x16x32_bf16 v[112:115], v[128:131], v[186:189], v[112:115]
	v_mfma_f32_16x16x32_bf16 v[112:115], v[132:135], v[190:193], v[112:115]
	v_mfma_f32_16x16x32_bf16 v[108:111], v[146:149], v[186:189], v[108:111]
	v_mfma_f32_16x16x32_bf16 v[108:111], v[158:161], v[190:193], v[108:111]
	v_mfma_f32_16x16x32_bf16 v[100:103], v[128:131], v[194:197], v[100:103]
	v_mfma_f32_16x16x32_bf16 v[100:103], v[132:135], v[198:201], v[100:103]
	v_mfma_f32_16x16x32_bf16 v[92:95], v[146:149], v[194:197], v[92:95]
	v_mfma_f32_16x16x32_bf16 v[92:95], v[158:161], v[198:201], v[92:95]
	v_mfma_f32_16x16x32_bf16 v[84:87], v[128:131], v[202:205], v[84:87]
	v_mfma_f32_16x16x32_bf16 v[84:87], v[132:135], v[206:209], v[84:87]
	v_mfma_f32_16x16x32_bf16 v[76:79], v[146:149], v[202:205], v[76:79]
	v_mfma_f32_16x16x32_bf16 v[76:79], v[158:161], v[206:209], v[76:79]
	s_setprio 0
	s_setprio 1
	v_mfma_f32_16x16x32_bf16 v[116:119], v[162:165], v[178:181], v[116:119]
	v_mfma_f32_16x16x32_bf16 v[116:119], v[166:169], v[182:185], v[116:119]
	v_mfma_f32_16x16x32_bf16 v[104:107], v[170:173], v[178:181], v[104:107]
	v_mfma_f32_16x16x32_bf16 v[104:107], v[174:177], v[182:185], v[104:107]
	v_mfma_f32_16x16x32_bf16 v[96:99], v[162:165], v[186:189], v[96:99]
	v_mfma_f32_16x16x32_bf16 v[96:99], v[166:169], v[190:193], v[96:99]
	v_mfma_f32_16x16x32_bf16 v[88:91], v[170:173], v[186:189], v[88:91]
	v_mfma_f32_16x16x32_bf16 v[88:91], v[174:177], v[190:193], v[88:91]
	v_mfma_f32_16x16x32_bf16 v[80:83], v[162:165], v[194:197], v[80:83]
	v_mfma_f32_16x16x32_bf16 v[80:83], v[166:169], v[198:201], v[80:83]
	v_mfma_f32_16x16x32_bf16 v[72:75], v[170:173], v[194:197], v[72:75]
	v_mfma_f32_16x16x32_bf16 v[72:75], v[174:177], v[198:201], v[72:75]
	s_setprio 2
	s_barrier
	v_mfma_f32_16x16x32_bf16 v[68:71], v[162:165], v[202:205], v[68:71]
	ds_read_b128 v[178:181], v155 offset:49152
	ds_read_b128 v[182:185], v155 offset:50176
	v_mfma_f32_16x16x32_bf16 v[68:71], v[166:169], v[206:209], v[68:71]
	ds_read_b128 v[186:189], v155 offset:51200
	ds_read_b128 v[190:193], v155 offset:52224
	v_mfma_f32_16x16x32_bf16 v[64:67], v[170:173], v[202:205], v[64:67]
	ds_read_b128 v[194:197], v155 offset:53248
	ds_read_b128 v[198:201], v155 offset:54272
	v_mfma_f32_16x16x32_bf16 v[64:67], v[174:177], v[206:209], v[64:67]
	s_setprio 0
	s_add_i32 s36, s36, s63
	s_mov_b32 m0, s36
	ds_read_b128 v[202:205], v155 offset:55296
	ds_read_b128 v[206:209], v155 offset:56320
	s_add_u32 s98, vcc_lo, s24
	s_addc_u32 s99, vcc_hi, s25
	global_load_lds_dwordx4 v138, s[98:99]
	s_add_i32 m0, s36, 0x2000
	s_add_i32 s36, s37, s63
	s_add_u32 s98, vcc_lo, s34
	s_addc_u32 s99, vcc_hi, s35
	global_load_lds_dwordx4 v138, s[98:99]
	s_mov_b32 m0, s36
	s_add_u32 s98, vcc_lo, s12
	s_addc_u32 s99, vcc_hi, s13
	global_load_lds_dwordx4 v138, s[98:99]
	s_add_i32 m0, s36, 0x2000
	s_nop 0
	s_add_u32 s98, vcc_lo, s18
	s_addc_u32 s99, vcc_hi, s19
	global_load_lds_dwordx4 v138, s[98:99]
	s_mov_b32 m0, s68
	s_nop 0
	s_add_u32 s98, s96, s24
	s_addc_u32 s99, s97, s25
	global_load_lds_dwordx4 v136, s[98:99]
	s_mov_b32 m0, s69
	s_nop 0
	s_add_u32 s98, s96, s34
	s_addc_u32 s99, s97, s35
	global_load_lds_dwordx4 v136, s[98:99]
	s_waitcnt vmcnt(8)
	s_waitcnt lgkmcnt(0)
	s_barrier
	s_setprio 1
	s_waitcnt lgkmcnt(0)
	v_mfma_f32_16x16x32_bf16 v[60:63], v[128:131], v[178:181], v[60:63]
	v_mfma_f32_16x16x32_bf16 v[60:63], v[132:135], v[182:185], v[60:63]
	v_mfma_f32_16x16x32_bf16 v[56:59], v[146:149], v[178:181], v[56:59]
	v_mfma_f32_16x16x32_bf16 v[56:59], v[158:161], v[182:185], v[56:59]
	v_mfma_f32_16x16x32_bf16 v[52:55], v[128:131], v[186:189], v[52:55]
	v_mfma_f32_16x16x32_bf16 v[52:55], v[132:135], v[190:193], v[52:55]
	v_mfma_f32_16x16x32_bf16 v[44:47], v[146:149], v[186:189], v[44:47]
	v_mfma_f32_16x16x32_bf16 v[44:47], v[158:161], v[190:193], v[44:47]
	v_mfma_f32_16x16x32_bf16 v[36:39], v[128:131], v[194:197], v[36:39]
	v_mfma_f32_16x16x32_bf16 v[36:39], v[132:135], v[198:201], v[36:39]
	v_mfma_f32_16x16x32_bf16 v[28:31], v[146:149], v[194:197], v[28:31]
	v_mfma_f32_16x16x32_bf16 v[28:31], v[158:161], v[198:201], v[28:31]
	v_mfma_f32_16x16x32_bf16 v[20:23], v[128:131], v[202:205], v[20:23]
	v_mfma_f32_16x16x32_bf16 v[20:23], v[132:135], v[206:209], v[20:23]
	v_mfma_f32_16x16x32_bf16 v[12:15], v[146:149], v[202:205], v[12:15]
	v_mfma_f32_16x16x32_bf16 v[12:15], v[158:161], v[206:209], v[12:15]
	s_setprio 0
	s_setprio 1
	v_mfma_f32_16x16x32_bf16 v[48:51], v[162:165], v[178:181], v[48:51]
	v_mfma_f32_16x16x32_bf16 v[48:51], v[166:169], v[182:185], v[48:51]
	v_mfma_f32_16x16x32_bf16 v[40:43], v[170:173], v[178:181], v[40:43]
	v_mfma_f32_16x16x32_bf16 v[40:43], v[174:177], v[182:185], v[40:43]
	v_mfma_f32_16x16x32_bf16 v[32:35], v[162:165], v[186:189], v[32:35]
	v_mfma_f32_16x16x32_bf16 v[32:35], v[166:169], v[190:193], v[32:35]
	v_mfma_f32_16x16x32_bf16 v[24:27], v[170:173], v[186:189], v[24:27]
	v_mfma_f32_16x16x32_bf16 v[24:27], v[174:177], v[190:193], v[24:27]
	v_mfma_f32_16x16x32_bf16 v[16:19], v[162:165], v[194:197], v[16:19]
	v_mfma_f32_16x16x32_bf16 v[16:19], v[166:169], v[198:201], v[16:19]
	v_mfma_f32_16x16x32_bf16 v[8:11], v[170:173], v[194:197], v[8:11]
	v_mfma_f32_16x16x32_bf16 v[8:11], v[174:177], v[198:201], v[8:11]
	s_setprio 2
	s_barrier
	v_mfma_f32_16x16x32_bf16 v[4:7], v[162:165], v[202:205], v[4:7]
	s_add_i32 s81, s81, 2
	s_add_u32 s22, s22, 0x100
	s_addc_u32 s80, s80, 0
	v_mfma_f32_16x16x32_bf16 v[4:7], v[166:169], v[206:209], v[4:7]
	s_add_u32 s78, s78, 0x100
	s_addc_u32 s79, s79, 0
	v_mfma_f32_16x16x32_bf16 v[0:3], v[170:173], v[202:205], v[0:3]
	v_mfma_f32_16x16x32_bf16 v[0:3], v[174:177], v[206:209], v[0:3]
	s_setprio 0
	s_cmp_gt_u32 s81, 61
	s_cbranch_scc0 .LBB0_298
	s_and_b64 vcc, exec, s[26:27]
	s_cbranch_vccz .LBB0_301
	s_barrier

.LBB0_627:
	ds_read_b128 v[128:131], v151
	ds_read_b128 v[142:145], v151 offset:1024
	ds_read_b128 v[146:149], v151 offset:2048
	ds_read_b128 v[154:157], v151 offset:3072
	ds_read_b128 v[158:161], v152
	ds_read_b128 v[162:165], v152 offset:1024
	ds_read_b128 v[166:169], v152 offset:2048
	ds_read_b128 v[170:173], v152 offset:3072
	s_add_u32 s50, s60, 0xfff00080
	s_addc_u32 s51, s61, -1
	s_cmp_eq_u32 s62, 60
	s_cselect_b32 s77, s5, s51
	s_cselect_b32 s76, s49, s50
	s_cselect_b32 s79, s47, s75
	s_cselect_b32 s78, s59, s74
	s_add_i32 m0, s20, 0xc000
	ds_read_b128 v[174:177], v153
	ds_read_b128 v[178:181], v153 offset:1024
	ds_read_b128 v[182:185], v153 offset:2048
	ds_read_b128 v[186:189], v153 offset:3072
	ds_read_b128 v[190:193], v153 offset:4096
	ds_read_b128 v[194:197], v153 offset:5120
	ds_read_b128 v[198:201], v153 offset:6144
	ds_read_b128 v[202:205], v153 offset:7168
	global_load_lds_dwordx4 v136, s[60:61]
	s_add_i32 m0, s20, 0xe000
	s_nop 0
	s_add_u32 s98, s60, s6
	s_addc_u32 s99, s61, s7
	global_load_lds_dwordx4 v136, s[98:99]
	s_waitcnt vmcnt(8)
	s_waitcnt lgkmcnt(0)
	s_barrier
	s_setprio 1
	s_waitcnt lgkmcnt(0)
	v_mfma_f32_16x16x32_bf16 v[124:127], v[128:131], v[174:177], v[124:127]
	v_mfma_f32_16x16x32_bf16 v[124:127], v[142:145], v[178:181], v[124:127]
	v_mfma_f32_16x16x32_bf16 v[120:123], v[146:149], v[174:177], v[120:123]
	v_mfma_f32_16x16x32_bf16 v[120:123], v[154:157], v[178:181], v[120:123]
	v_mfma_f32_16x16x32_bf16 v[116:119], v[128:131], v[182:185], v[116:119]
	v_mfma_f32_16x16x32_bf16 v[116:119], v[142:145], v[186:189], v[116:119]
	v_mfma_f32_16x16x32_bf16 v[112:115], v[146:149], v[182:185], v[112:115]
	v_mfma_f32_16x16x32_bf16 v[112:115], v[154:157], v[186:189], v[112:115]
	v_mfma_f32_16x16x32_bf16 v[108:111], v[128:131], v[190:193], v[108:111]
	v_mfma_f32_16x16x32_bf16 v[108:111], v[142:145], v[194:197], v[108:111]
	v_mfma_f32_16x16x32_bf16 v[104:107], v[146:149], v[190:193], v[104:107]
	v_mfma_f32_16x16x32_bf16 v[104:107], v[154:157], v[194:197], v[104:107]
	v_mfma_f32_16x16x32_bf16 v[100:103], v[128:131], v[198:201], v[100:103]
	v_mfma_f32_16x16x32_bf16 v[100:103], v[142:145], v[202:205], v[100:103]
	v_mfma_f32_16x16x32_bf16 v[96:99], v[146:149], v[198:201], v[96:99]
	v_mfma_f32_16x16x32_bf16 v[96:99], v[154:157], v[202:205], v[96:99]
	s_setprio 0
	s_setprio 1
	v_mfma_f32_16x16x32_bf16 v[92:95], v[158:161], v[174:177], v[92:95]
	v_mfma_f32_16x16x32_bf16 v[92:95], v[162:165], v[178:181], v[92:95]
	v_mfma_f32_16x16x32_bf16 v[88:91], v[166:169], v[174:177], v[88:91]
	v_mfma_f32_16x16x32_bf16 v[88:91], v[170:173], v[178:181], v[88:91]
	v_mfma_f32_16x16x32_bf16 v[84:87], v[158:161], v[182:185], v[84:87]
	v_mfma_f32_16x16x32_bf16 v[84:87], v[162:165], v[186:189], v[84:87]
	v_mfma_f32_16x16x32_bf16 v[80:83], v[166:169], v[182:185], v[80:83]
	v_mfma_f32_16x16x32_bf16 v[80:83], v[170:173], v[186:189], v[80:83]
	v_mfma_f32_16x16x32_bf16 v[76:79], v[158:161], v[190:193], v[76:79]
	v_mfma_f32_16x16x32_bf16 v[76:79], v[162:165], v[194:197], v[76:79]
	v_mfma_f32_16x16x32_bf16 v[72:75], v[166:169], v[190:193], v[72:75]
	v_mfma_f32_16x16x32_bf16 v[72:75], v[170:173], v[194:197], v[72:75]
	s_setprio 2
	s_barrier
	v_mfma_f32_16x16x32_bf16 v[68:71], v[158:161], v[198:201], v[68:71]
	ds_read_b128 v[174:177], v153 offset:16384
	ds_read_b128 v[178:181], v153 offset:17408
	v_mfma_f32_16x16x32_bf16 v[68:71], v[162:165], v[202:205], v[68:71]
	ds_read_b128 v[182:185], v153 offset:18432
	ds_read_b128 v[186:189], v153 offset:19456
	v_mfma_f32_16x16x32_bf16 v[64:67], v[166:169], v[198:201], v[64:67]
	ds_read_b128 v[190:193], v153 offset:20480
	ds_read_b128 v[194:197], v153 offset:21504
	v_mfma_f32_16x16x32_bf16 v[64:67], v[170:173], v[202:205], v[64:67]
	s_setprio 0
	s_add_i32 s50, s72, s14
	s_mov_b32 m0, s50
	ds_read_b128 v[198:201], v153 offset:22528
	ds_read_b128 v[202:205], v153 offset:23552
	global_load_lds_dwordx4 v134, s[78:79]
	s_add_i32 m0, s50, 0x2000
	s_add_i32 s50, s73, s14
	s_add_u32 s98, s78, s6
	s_addc_u32 s99, s79, s7
	global_load_lds_dwordx4 v134, s[98:99]
	s_mov_b32 m0, s50
	s_nop 0
	s_add_u32 s98, s78, s8
	s_addc_u32 s99, s79, s9
	global_load_lds_dwordx4 v134, s[98:99]
	s_add_i32 m0, s50, 0x2000
	s_nop 0
	s_add_u32 s98, s78, s10
	s_addc_u32 s99, s79, s11
	global_load_lds_dwordx4 v134, s[98:99]
	s_mov_b32 m0, s20
	s_nop 0
	global_load_lds_dwordx4 v132, s[76:77]
	s_mov_b32 m0, s21
	s_nop 0
	s_add_u32 s98, s76, s6
	s_addc_u32 s99, s77, s7
	global_load_lds_dwordx4 v132, s[98:99]
	s_waitcnt vmcnt(8)
	s_waitcnt lgkmcnt(0)
	s_barrier
	s_setprio 1
	s_waitcnt lgkmcnt(0)
	v_mfma_f32_16x16x32_bf16 v[60:63], v[128:131], v[174:177], v[60:63]
	v_mfma_f32_16x16x32_bf16 v[60:63], v[142:145], v[178:181], v[60:63]
	v_mfma_f32_16x16x32_bf16 v[56:59], v[146:149], v[174:177], v[56:59]
	v_mfma_f32_16x16x32_bf16 v[56:59], v[154:157], v[178:181], v[56:59]
	v_mfma_f32_16x16x32_bf16 v[52:55], v[128:131], v[182:185], v[52:55]
	v_mfma_f32_16x16x32_bf16 v[52:55], v[142:145], v[186:189], v[52:55]
	v_mfma_f32_16x16x32_bf16 v[48:51], v[146:149], v[182:185], v[48:51]
	v_mfma_f32_16x16x32_bf16 v[48:51], v[154:157], v[186:189], v[48:51]
	v_mfma_f32_16x16x32_bf16 v[44:47], v[128:131], v[190:193], v[44:47]
	v_mfma_f32_16x16x32_bf16 v[44:47], v[142:145], v[194:197], v[44:47]
	v_mfma_f32_16x16x32_bf16 v[40:43], v[146:149], v[190:193], v[40:43]
	v_mfma_f32_16x16x32_bf16 v[40:43], v[154:157], v[194:197], v[40:43]
	v_mfma_f32_16x16x32_bf16 v[36:39], v[128:131], v[198:201], v[36:39]
	v_mfma_f32_16x16x32_bf16 v[36:39], v[142:145], v[202:205], v[36:39]
	v_mfma_f32_16x16x32_bf16 v[32:35], v[146:149], v[198:201], v[32:35]
	v_mfma_f32_16x16x32_bf16 v[32:35], v[154:157], v[202:205], v[32:35]
	s_setprio 0
	s_setprio 1
	v_mfma_f32_16x16x32_bf16 v[28:31], v[158:161], v[174:177], v[28:31]
	v_mfma_f32_16x16x32_bf16 v[28:31], v[162:165], v[178:181], v[28:31]
	v_mfma_f32_16x16x32_bf16 v[24:27], v[166:169], v[174:177], v[24:27]
	v_mfma_f32_16x16x32_bf16 v[24:27], v[170:173], v[178:181], v[24:27]
	v_mfma_f32_16x16x32_bf16 v[20:23], v[158:161], v[182:185], v[20:23]
	v_mfma_f32_16x16x32_bf16 v[20:23], v[162:165], v[186:189], v[20:23]
	v_mfma_f32_16x16x32_bf16 v[16:19], v[166:169], v[182:185], v[16:19]
	v_mfma_f32_16x16x32_bf16 v[16:19], v[170:173], v[186:189], v[16:19]
	v_mfma_f32_16x16x32_bf16 v[12:15], v[158:161], v[190:193], v[12:15]
	v_mfma_f32_16x16x32_bf16 v[12:15], v[162:165], v[194:197], v[12:15]
	v_mfma_f32_16x16x32_bf16 v[8:11], v[166:169], v[190:193], v[8:11]
	v_mfma_f32_16x16x32_bf16 v[8:11], v[170:173], v[194:197], v[8:11]
	s_setprio 2
	s_barrier
	v_mfma_f32_16x16x32_bf16 v[4:7], v[158:161], v[198:201], v[4:7]
	ds_read_b128 v[174:177], v153 offset:32768
	ds_read_b128 v[178:181], v153 offset:33792
	v_mfma_f32_16x16x32_bf16 v[4:7], v[162:165], v[202:205], v[4:7]
	ds_read_b128 v[182:185], v153 offset:34816
	ds_read_b128 v[186:189], v153 offset:35840
	v_mfma_f32_16x16x32_bf16 v[0:3], v[166:169], v[198:201], v[0:3]
	ds_read_b128 v[190:193], v153 offset:36864
	ds_read_b128 v[194:197], v153 offset:37888
	v_mfma_f32_16x16x32_bf16 v[0:3], v[170:173], v[202:205], v[0:3]
	s_setprio 0
	s_add_i32 s50, 0, 0x18000
	s_add_i32 s51, 0, 0x1c000
	v_add_u32_e32 v154, s50, v150
	v_add_u32_e32 v170, s51, v150
	ds_read_b128 v[128:131], v154
	ds_read_b128 v[142:145], v154 offset:1024
	ds_read_b128 v[146:149], v154 offset:2048
	ds_read_b128 v[154:157], v154 offset:3072
	ds_read_b128 v[158:161], v170
	ds_read_b128 v[162:165], v170 offset:1024
	ds_read_b128 v[166:169], v170 offset:2048
	ds_read_b128 v[170:173], v170 offset:3072
	s_mov_b32 m0, s33
	ds_read_b128 v[198:201], v153 offset:38912
	ds_read_b128 v[202:205], v153 offset:39936
	s_add_u32 s98, s76, s8
	s_addc_u32 s99, s77, s9
	global_load_lds_dwordx4 v132, s[98:99]
	s_mov_b32 m0, s64
	s_nop 0
	s_add_u32 s98, s76, s10
	s_addc_u32 s99, s77, s11
	global_load_lds_dwordx4 v132, s[98:99]
	s_waitcnt vmcnt(8)
	s_waitcnt lgkmcnt(0)
	s_barrier
	s_setprio 1
	s_waitcnt lgkmcnt(0)
	v_mfma_f32_16x16x32_bf16 v[124:127], v[128:131], v[174:177], v[124:127]
	v_mfma_f32_16x16x32_bf16 v[124:127], v[142:145], v[178:181], v[124:127]
	v_mfma_f32_16x16x32_bf16 v[120:123], v[146:149], v[174:177], v[120:123]
	v_mfma_f32_16x16x32_bf16 v[120:123], v[154:157], v[178:181], v[120:123]
	v_mfma_f32_16x16x32_bf16 v[116:119], v[128:131], v[182:185], v[116:119]
	v_mfma_f32_16x16x32_bf16 v[116:119], v[142:145], v[186:189], v[116:119]
	v_mfma_f32_16x16x32_bf16 v[112:115], v[146:149], v[182:185], v[112:115]
	v_mfma_f32_16x16x32_bf16 v[112:115], v[154:157], v[186:189], v[112:115]
	v_mfma_f32_16x16x32_bf16 v[108:111], v[128:131], v[190:193], v[108:111]
	v_mfma_f32_16x16x32_bf16 v[108:111], v[142:145], v[194:197], v[108:111]
	v_mfma_f32_16x16x32_bf16 v[104:107], v[146:149], v[190:193], v[104:107]
	v_mfma_f32_16x16x32_bf16 v[104:107], v[154:157], v[194:197], v[104:107]
	v_mfma_f32_16x16x32_bf16 v[100:103], v[128:131], v[198:201], v[100:103]
	v_mfma_f32_16x16x32_bf16 v[100:103], v[142:145], v[202:205], v[100:103]
	v_mfma_f32_16x16x32_bf16 v[96:99], v[146:149], v[198:201], v[96:99]
	v_mfma_f32_16x16x32_bf16 v[96:99], v[154:157], v[202:205], v[96:99]
	s_setprio 0
	s_setprio 1
	v_mfma_f32_16x16x32_bf16 v[92:95], v[158:161], v[174:177], v[92:95]
	v_mfma_f32_16x16x32_bf16 v[92:95], v[162:165], v[178:181], v[92:95]
	v_mfma_f32_16x16x32_bf16 v[88:91], v[166:169], v[174:177], v[88:91]
	v_mfma_f32_16x16x32_bf16 v[88:91], v[170:173], v[178:181], v[88:91]
	v_mfma_f32_16x16x32_bf16 v[84:87], v[158:161], v[182:185], v[84:87]
	v_mfma_f32_16x16x32_bf16 v[84:87], v[162:165], v[186:189], v[84:87]
	v_mfma_f32_16x16x32_bf16 v[80:83], v[166:169], v[182:185], v[80:83]
	v_mfma_f32_16x16x32_bf16 v[80:83], v[170:173], v[186:189], v[80:83]
	v_mfma_f32_16x16x32_bf16 v[76:79], v[158:161], v[190:193], v[76:79]
	v_mfma_f32_16x16x32_bf16 v[76:79], v[162:165], v[194:197], v[76:79]
	v_mfma_f32_16x16x32_bf16 v[72:75], v[166:169], v[190:193], v[72:75]
	v_mfma_f32_16x16x32_bf16 v[72:75], v[170:173], v[194:197], v[72:75]
	s_setprio 2
	s_barrier
	v_mfma_f32_16x16x32_bf16 v[68:71], v[158:161], v[198:201], v[68:71]
	ds_read_b128 v[174:177], v153 offset:49152
	ds_read_b128 v[178:181], v153 offset:50176
	v_mfma_f32_16x16x32_bf16 v[68:71], v[162:165], v[202:205], v[68:71]
	ds_read_b128 v[182:185], v153 offset:51200
	ds_read_b128 v[186:189], v153 offset:52224
	v_mfma_f32_16x16x32_bf16 v[64:67], v[166:169], v[198:201], v[64:67]
	ds_read_b128 v[190:193], v153 offset:53248
	ds_read_b128 v[194:197], v153 offset:54272
	v_mfma_f32_16x16x32_bf16 v[64:67], v[170:173], v[202:205], v[64:67]
	s_setprio 0
	s_add_i32 s50, s50, s14
	s_mov_b32 m0, s50
	ds_read_b128 v[198:201], v153 offset:55296
	ds_read_b128 v[202:205], v153 offset:56320
	s_add_u32 s98, s78, s24
	s_addc_u32 s99, s79, s25
	global_load_lds_dwordx4 v134, s[98:99]
	s_add_i32 m0, s50, 0x2000
	s_add_i32 s50, s51, s14
	s_add_u32 s98, s78, s34
	s_addc_u32 s99, s79, s35
	global_load_lds_dwordx4 v134, s[98:99]
	s_mov_b32 m0, s50
	s_add_u32 s98, s78, s36
	s_addc_u32 s99, s79, s37
	global_load_lds_dwordx4 v134, s[98:99]
	s_add_i32 m0, s50, 0x2000
	s_nop 0
	s_add_u32 s98, s78, s38
	s_addc_u32 s99, s79, s39
	global_load_lds_dwordx4 v134, s[98:99]
	s_mov_b32 m0, s66
	s_nop 0
	s_add_u32 s98, s76, s24
	s_addc_u32 s99, s77, s25
	global_load_lds_dwordx4 v132, s[98:99]
	s_mov_b32 m0, s67
	s_nop 0
	s_add_u32 s98, s76, s34
	s_addc_u32 s99, s77, s35
	global_load_lds_dwordx4 v132, s[98:99]
	s_waitcnt vmcnt(8)
	s_waitcnt lgkmcnt(0)
	s_barrier
	s_setprio 1
	s_waitcnt lgkmcnt(0)
	v_mfma_f32_16x16x32_bf16 v[60:63], v[128:131], v[174:177], v[60:63]
	v_mfma_f32_16x16x32_bf16 v[60:63], v[142:145], v[178:181], v[60:63]
	v_mfma_f32_16x16x32_bf16 v[56:59], v[146:149], v[174:177], v[56:59]
	v_mfma_f32_16x16x32_bf16 v[56:59], v[154:157], v[178:181], v[56:59]
	v_mfma_f32_16x16x32_bf16 v[52:55], v[128:131], v[182:185], v[52:55]
	v_mfma_f32_16x16x32_bf16 v[52:55], v[142:145], v[186:189], v[52:55]
	v_mfma_f32_16x16x32_bf16 v[48:51], v[146:149], v[182:185], v[48:51]
	v_mfma_f32_16x16x32_bf16 v[48:51], v[154:157], v[186:189], v[48:51]
	v_mfma_f32_16x16x32_bf16 v[44:47], v[128:131], v[190:193], v[44:47]
	v_mfma_f32_16x16x32_bf16 v[44:47], v[142:145], v[194:197], v[44:47]
	v_mfma_f32_16x16x32_bf16 v[40:43], v[146:149], v[190:193], v[40:43]
	v_mfma_f32_16x16x32_bf16 v[40:43], v[154:157], v[194:197], v[40:43]
	v_mfma_f32_16x16x32_bf16 v[36:39], v[128:131], v[198:201], v[36:39]
	v_mfma_f32_16x16x32_bf16 v[36:39], v[142:145], v[202:205], v[36:39]
	v_mfma_f32_16x16x32_bf16 v[32:35], v[146:149], v[198:201], v[32:35]
	v_mfma_f32_16x16x32_bf16 v[32:35], v[154:157], v[202:205], v[32:35]
	s_setprio 0
	s_setprio 1
	v_mfma_f32_16x16x32_bf16 v[28:31], v[158:161], v[174:177], v[28:31]
	v_mfma_f32_16x16x32_bf16 v[28:31], v[162:165], v[178:181], v[28:31]
	v_mfma_f32_16x16x32_bf16 v[24:27], v[166:169], v[174:177], v[24:27]
	v_mfma_f32_16x16x32_bf16 v[24:27], v[170:173], v[178:181], v[24:27]
	v_mfma_f32_16x16x32_bf16 v[20:23], v[158:161], v[182:185], v[20:23]
	v_mfma_f32_16x16x32_bf16 v[20:23], v[162:165], v[186:189], v[20:23]
	v_mfma_f32_16x16x32_bf16 v[16:19], v[166:169], v[182:185], v[16:19]
	v_mfma_f32_16x16x32_bf16 v[16:19], v[170:173], v[186:189], v[16:19]
	v_mfma_f32_16x16x32_bf16 v[12:15], v[158:161], v[190:193], v[12:15]
	v_mfma_f32_16x16x32_bf16 v[12:15], v[162:165], v[194:197], v[12:15]
	v_mfma_f32_16x16x32_bf16 v[8:11], v[166:169], v[190:193], v[8:11]
	v_mfma_f32_16x16x32_bf16 v[8:11], v[170:173], v[194:197], v[8:11]
	s_setprio 2
	s_barrier
	v_mfma_f32_16x16x32_bf16 v[4:7], v[158:161], v[198:201], v[4:7]
	s_add_i32 s62, s62, 2
	s_add_u32 s74, s74, 0x100
	s_addc_u32 s75, s75, 0
	v_mfma_f32_16x16x32_bf16 v[4:7], v[162:165], v[202:205], v[4:7]
	s_add_u32 s60, s60, 0x100
	s_addc_u32 s61, s61, 0
	v_mfma_f32_16x16x32_bf16 v[0:3], v[166:169], v[198:201], v[0:3]
	v_mfma_f32_16x16x32_bf16 v[0:3], v[170:173], v[202:205], v[0:3]
	s_setprio 0
	s_cmp_gt_u32 s62, 61
	s_cbranch_scc0 .LBB0_627
	s_and_b64 vcc, exec, s[40:41]
	s_cbranch_vccz .LBB0_630
	s_barrier

.LBB0_800:
	ds_read_b128 v[128:131], v187
	ds_read_b128 v[132:135], v187 offset:1024
	ds_read_b128 v[136:139], v187 offset:2048
	ds_read_b128 v[140:143], v187 offset:3072
	ds_read_b128 v[144:147], v188
	ds_read_b128 v[148:151], v188 offset:1024
	ds_read_b128 v[152:155], v188 offset:2048
	ds_read_b128 v[156:159], v188 offset:3072
	s_add_u32 s9, s6, 0xfff80080
	s_addc_u32 s50, s7, -1
	s_cmp_eq_u32 s8, 28
	s_cselect_b32 vcc_hi, s5, s50
	s_cselect_b32 vcc_lo, s10, s9
	s_cselect_b32 s51, s11, s78
	s_cselect_b32 s50, s73, s75
	s_add_i32 m0, s65, 0xc000
	ds_read_b128 v[160:163], v189
	ds_read_b128 v[164:167], v189 offset:1024
	ds_read_b128 v[168:171], v189 offset:2048
	ds_read_b128 v[192:195], v189 offset:3072
	ds_read_b128 v[196:199], v189 offset:4096
	ds_read_b128 v[200:203], v189 offset:5120
	ds_read_b128 v[204:207], v189 offset:6144
	ds_read_b128 v[208:211], v189 offset:7168
	global_load_lds_dwordx4 v178, s[6:7]
	s_add_i32 m0, s65, 0xe000
	s_nop 0
	s_add_u32 s98, s6, s36
	s_addc_u32 s99, s7, s37
	global_load_lds_dwordx4 v178, s[98:99]
	s_waitcnt vmcnt(8)
	s_waitcnt lgkmcnt(0)
	s_barrier
	s_setprio 1
	s_waitcnt lgkmcnt(0)
	v_mfma_i32_16x16x64_i8 v[84:87], v[128:131], v[160:163], v[84:87]
	v_mfma_i32_16x16x64_i8 v[84:87], v[132:135], v[164:167], v[84:87]
	v_mfma_i32_16x16x64_i8 v[16:19], v[136:139], v[160:163], v[16:19]
	v_mfma_i32_16x16x64_i8 v[16:19], v[140:143], v[164:167], v[16:19]
	v_mfma_i32_16x16x64_i8 v[88:91], v[128:131], v[168:171], v[88:91]
	v_mfma_i32_16x16x64_i8 v[88:91], v[132:135], v[192:195], v[88:91]
	v_mfma_i32_16x16x64_i8 v[20:23], v[136:139], v[168:171], v[20:23]
	v_mfma_i32_16x16x64_i8 v[20:23], v[140:143], v[192:195], v[20:23]
	v_mfma_i32_16x16x64_i8 v[92:95], v[128:131], v[196:199], v[92:95]
	v_mfma_i32_16x16x64_i8 v[92:95], v[132:135], v[200:203], v[92:95]
	v_mfma_i32_16x16x64_i8 v[24:27], v[136:139], v[196:199], v[24:27]
	v_mfma_i32_16x16x64_i8 v[24:27], v[140:143], v[200:203], v[24:27]
	v_mfma_i32_16x16x64_i8 v[96:99], v[128:131], v[204:207], v[96:99]
	v_mfma_i32_16x16x64_i8 v[96:99], v[132:135], v[208:211], v[96:99]
	v_mfma_i32_16x16x64_i8 v[28:31], v[136:139], v[204:207], v[28:31]
	v_mfma_i32_16x16x64_i8 v[28:31], v[140:143], v[208:211], v[28:31]
	s_setprio 0
	s_setprio 1
	v_mfma_i32_16x16x64_i8 v[124:127], v[144:147], v[160:163], v[124:127]
	v_mfma_i32_16x16x64_i8 v[124:127], v[148:151], v[164:167], v[124:127]
	v_mfma_i32_16x16x64_i8 v[68:71], v[152:155], v[160:163], v[68:71]
	v_mfma_i32_16x16x64_i8 v[68:71], v[156:159], v[164:167], v[68:71]
	v_mfma_i32_16x16x64_i8 v[120:123], v[144:147], v[168:171], v[120:123]
	v_mfma_i32_16x16x64_i8 v[120:123], v[148:151], v[192:195], v[120:123]
	v_mfma_i32_16x16x64_i8 v[72:75], v[152:155], v[168:171], v[72:75]
	v_mfma_i32_16x16x64_i8 v[72:75], v[156:159], v[192:195], v[72:75]
	v_mfma_i32_16x16x64_i8 v[116:119], v[144:147], v[196:199], v[116:119]
	v_mfma_i32_16x16x64_i8 v[116:119], v[148:151], v[200:203], v[116:119]
	v_mfma_i32_16x16x64_i8 v[80:83], v[152:155], v[196:199], v[80:83]
	v_mfma_i32_16x16x64_i8 v[80:83], v[156:159], v[200:203], v[80:83]
	s_setprio 2
	s_barrier
	v_mfma_i32_16x16x64_i8 v[112:115], v[144:147], v[204:207], v[112:115]
	ds_read_b128 v[160:163], v189 offset:16384
	ds_read_b128 v[164:167], v189 offset:17408
	v_mfma_i32_16x16x64_i8 v[112:115], v[148:151], v[208:211], v[112:115]
	ds_read_b128 v[168:171], v189 offset:18432
	ds_read_b128 v[192:195], v189 offset:19456
	v_mfma_i32_16x16x64_i8 v[60:63], v[152:155], v[204:207], v[60:63]
	ds_read_b128 v[196:199], v189 offset:20480
	ds_read_b128 v[200:203], v189 offset:21504
	v_mfma_i32_16x16x64_i8 v[60:63], v[156:159], v[208:211], v[60:63]
	s_setprio 0
	s_add_i32 s9, s80, s33
	s_mov_b64 s[100:101], s[50:51]
	s_mov_b32 m0, s9
	ds_read_b128 v[204:207], v189 offset:22528
	ds_read_b128 v[208:211], v189 offset:23552
	global_load_lds_dwordx4 v174, s[50:51]
	s_add_i32 m0, s9, 0x2000
	s_add_i32 s9, s81, s33
	s_add_u32 s98, s50, s36
	s_addc_u32 s99, s51, s37
	global_load_lds_dwordx4 v174, s[98:99]
	s_mov_b32 m0, s9
	s_nop 0
	s_add_u32 s98, s50, s38
	s_addc_u32 s99, s51, s39
	global_load_lds_dwordx4 v174, s[98:99]
	s_add_i32 m0, s9, 0x2000
	s_nop 0
	s_add_u32 s98, s50, s40
	s_addc_u32 s99, s51, s41
	global_load_lds_dwordx4 v174, s[98:99]
	s_mov_b32 m0, s65
	s_nop 0
	global_load_lds_dwordx4 v172, vcc
	s_mov_b32 m0, s67
	s_nop 0
	s_add_u32 s98, vcc_lo, s36
	s_addc_u32 s99, vcc_hi, s37
	global_load_lds_dwordx4 v172, s[98:99]
	s_waitcnt vmcnt(8)
	s_waitcnt lgkmcnt(0)
	s_barrier
	s_setprio 1
	s_waitcnt lgkmcnt(0)
	v_mfma_i32_16x16x64_i8 v[48:51], v[128:131], v[160:163], v[48:51]
	v_mfma_i32_16x16x64_i8 v[48:51], v[132:135], v[164:167], v[48:51]
	v_mfma_i32_16x16x64_i8 v[0:3], v[136:139], v[160:163], v[0:3]
	v_mfma_i32_16x16x64_i8 v[0:3], v[140:143], v[164:167], v[0:3]
	v_mfma_i32_16x16x64_i8 v[52:55], v[128:131], v[168:171], v[52:55]
	v_mfma_i32_16x16x64_i8 v[52:55], v[132:135], v[192:195], v[52:55]
	v_mfma_i32_16x16x64_i8 v[4:7], v[136:139], v[168:171], v[4:7]
	v_mfma_i32_16x16x64_i8 v[4:7], v[140:143], v[192:195], v[4:7]
	v_mfma_i32_16x16x64_i8 v[56:59], v[128:131], v[196:199], v[56:59]
	v_mfma_i32_16x16x64_i8 v[56:59], v[132:135], v[200:203], v[56:59]
	v_mfma_i32_16x16x64_i8 v[8:11], v[136:139], v[196:199], v[8:11]
	v_mfma_i32_16x16x64_i8 v[8:11], v[140:143], v[200:203], v[8:11]
	v_mfma_i32_16x16x64_i8 v[64:67], v[128:131], v[204:207], v[64:67]
	v_mfma_i32_16x16x64_i8 v[64:67], v[132:135], v[208:211], v[64:67]
	v_mfma_i32_16x16x64_i8 v[12:15], v[136:139], v[204:207], v[12:15]
	v_mfma_i32_16x16x64_i8 v[12:15], v[140:143], v[208:211], v[12:15]
	s_setprio 0
	s_setprio 1
	v_mfma_i32_16x16x64_i8 v[108:111], v[144:147], v[160:163], v[108:111]
	v_mfma_i32_16x16x64_i8 v[108:111], v[148:151], v[164:167], v[108:111]
	v_mfma_i32_16x16x64_i8 v[44:47], v[152:155], v[160:163], v[44:47]
	v_mfma_i32_16x16x64_i8 v[44:47], v[156:159], v[164:167], v[44:47]
	v_mfma_i32_16x16x64_i8 v[104:107], v[144:147], v[168:171], v[104:107]
	v_mfma_i32_16x16x64_i8 v[104:107], v[148:151], v[192:195], v[104:107]
	v_mfma_i32_16x16x64_i8 v[40:43], v[152:155], v[168:171], v[40:43]
	v_mfma_i32_16x16x64_i8 v[40:43], v[156:159], v[192:195], v[40:43]
	v_mfma_i32_16x16x64_i8 v[100:103], v[144:147], v[196:199], v[100:103]
	v_mfma_i32_16x16x64_i8 v[100:103], v[148:151], v[200:203], v[100:103]
	v_mfma_i32_16x16x64_i8 v[32:35], v[152:155], v[196:199], v[32:35]
	v_mfma_i32_16x16x64_i8 v[32:35], v[156:159], v[200:203], v[32:35]
	s_setprio 2
	s_barrier
	v_mfma_i32_16x16x64_i8 v[76:79], v[144:147], v[204:207], v[76:79]
	ds_read_b128 v[160:163], v189 offset:32768
	ds_read_b128 v[164:167], v189 offset:33792
	v_mfma_i32_16x16x64_i8 v[76:79], v[148:151], v[208:211], v[76:79]
	ds_read_b128 v[168:171], v189 offset:34816
	ds_read_b128 v[192:195], v189 offset:35840
	v_mfma_i32_16x16x64_i8 v[36:39], v[152:155], v[204:207], v[36:39]
	ds_read_b128 v[196:199], v189 offset:36864
	ds_read_b128 v[200:203], v189 offset:37888
	v_mfma_i32_16x16x64_i8 v[36:39], v[156:159], v[208:211], v[36:39]
	s_setprio 0
	s_add_i32 s9, 0, 0x18000
	s_add_i32 s50, 0, 0x1c000
	v_add_u32_e32 v140, s9, v186
	v_add_u32_e32 v156, s50, v186
	ds_read_b128 v[128:131], v140
	ds_read_b128 v[132:135], v140 offset:1024
	ds_read_b128 v[136:139], v140 offset:2048
	ds_read_b128 v[140:143], v140 offset:3072
	ds_read_b128 v[144:147], v156
	ds_read_b128 v[148:151], v156 offset:1024
	ds_read_b128 v[152:155], v156 offset:2048
	ds_read_b128 v[156:159], v156 offset:3072
	s_mov_b32 m0, s71
	ds_read_b128 v[204:207], v189 offset:38912
	ds_read_b128 v[208:211], v189 offset:39936
	s_add_u32 s98, vcc_lo, s38
	s_addc_u32 s99, vcc_hi, s39
	global_load_lds_dwordx4 v172, s[98:99]
	s_mov_b32 m0, s82
	s_nop 0
	s_add_u32 s98, vcc_lo, s40
	s_addc_u32 s99, vcc_hi, s41
	global_load_lds_dwordx4 v172, s[98:99]
	s_waitcnt vmcnt(8)
	s_waitcnt lgkmcnt(0)
	s_barrier
	s_setprio 1
	s_waitcnt lgkmcnt(0)
	v_mfma_i32_16x16x64_i8 v[84:87], v[128:131], v[160:163], v[84:87]
	v_mfma_i32_16x16x64_i8 v[84:87], v[132:135], v[164:167], v[84:87]
	v_mfma_i32_16x16x64_i8 v[16:19], v[136:139], v[160:163], v[16:19]
	v_mfma_i32_16x16x64_i8 v[16:19], v[140:143], v[164:167], v[16:19]
	v_mfma_i32_16x16x64_i8 v[88:91], v[128:131], v[168:171], v[88:91]
	v_mfma_i32_16x16x64_i8 v[88:91], v[132:135], v[192:195], v[88:91]
	v_mfma_i32_16x16x64_i8 v[20:23], v[136:139], v[168:171], v[20:23]
	v_mfma_i32_16x16x64_i8 v[20:23], v[140:143], v[192:195], v[20:23]
	v_mfma_i32_16x16x64_i8 v[92:95], v[128:131], v[196:199], v[92:95]
	v_mfma_i32_16x16x64_i8 v[92:95], v[132:135], v[200:203], v[92:95]
	v_mfma_i32_16x16x64_i8 v[24:27], v[136:139], v[196:199], v[24:27]
	v_mfma_i32_16x16x64_i8 v[24:27], v[140:143], v[200:203], v[24:27]
	v_mfma_i32_16x16x64_i8 v[96:99], v[128:131], v[204:207], v[96:99]
	v_mfma_i32_16x16x64_i8 v[96:99], v[132:135], v[208:211], v[96:99]
	v_mfma_i32_16x16x64_i8 v[28:31], v[136:139], v[204:207], v[28:31]
	v_mfma_i32_16x16x64_i8 v[28:31], v[140:143], v[208:211], v[28:31]
	s_setprio 0
	s_setprio 1
	v_mfma_i32_16x16x64_i8 v[124:127], v[144:147], v[160:163], v[124:127]
	v_mfma_i32_16x16x64_i8 v[124:127], v[148:151], v[164:167], v[124:127]
	v_mfma_i32_16x16x64_i8 v[68:71], v[152:155], v[160:163], v[68:71]
	v_mfma_i32_16x16x64_i8 v[68:71], v[156:159], v[164:167], v[68:71]
	v_mfma_i32_16x16x64_i8 v[120:123], v[144:147], v[168:171], v[120:123]
	v_mfma_i32_16x16x64_i8 v[120:123], v[148:151], v[192:195], v[120:123]
	v_mfma_i32_16x16x64_i8 v[72:75], v[152:155], v[168:171], v[72:75]
	v_mfma_i32_16x16x64_i8 v[72:75], v[156:159], v[192:195], v[72:75]
	v_mfma_i32_16x16x64_i8 v[116:119], v[144:147], v[196:199], v[116:119]
	v_mfma_i32_16x16x64_i8 v[116:119], v[148:151], v[200:203], v[116:119]
	v_mfma_i32_16x16x64_i8 v[80:83], v[152:155], v[196:199], v[80:83]
	v_mfma_i32_16x16x64_i8 v[80:83], v[156:159], v[200:203], v[80:83]
	s_setprio 2
	s_barrier
	v_mfma_i32_16x16x64_i8 v[112:115], v[144:147], v[204:207], v[112:115]
	ds_read_b128 v[160:163], v189 offset:49152
	ds_read_b128 v[164:167], v189 offset:50176
	v_mfma_i32_16x16x64_i8 v[112:115], v[148:151], v[208:211], v[112:115]
	ds_read_b128 v[168:171], v189 offset:51200
	ds_read_b128 v[192:195], v189 offset:52224
	v_mfma_i32_16x16x64_i8 v[60:63], v[152:155], v[204:207], v[60:63]
	ds_read_b128 v[196:199], v189 offset:53248
	ds_read_b128 v[200:203], v189 offset:54272
	v_mfma_i32_16x16x64_i8 v[60:63], v[156:159], v[208:211], v[60:63]
	s_setprio 0
	s_add_i32 s9, s9, s33
	s_mov_b32 m0, s9
	ds_read_b128 v[204:207], v189 offset:55296
	ds_read_b128 v[208:211], v189 offset:56320
	s_add_u32 s98, s100, s44
	s_addc_u32 s99, s101, s45
	global_load_lds_dwordx4 v174, s[98:99]
	s_add_i32 m0, s9, 0x2000
	s_add_i32 s9, s50, s33
	s_add_u32 s98, s100, s46
	s_addc_u32 s99, s101, s47
	global_load_lds_dwordx4 v174, s[98:99]
	s_mov_b32 m0, s9
	s_add_u32 s98, s100, s48
	s_addc_u32 s99, s101, s49
	global_load_lds_dwordx4 v174, s[98:99]
	s_add_i32 m0, s9, 0x2000
	s_nop 0
	s_add_u32 s98, s100, s52
	s_addc_u32 s99, s101, s53
	global_load_lds_dwordx4 v174, s[98:99]
	s_mov_b32 m0, s90
	s_nop 0
	s_add_u32 s98, vcc_lo, s44
	s_addc_u32 s99, vcc_hi, s45
	global_load_lds_dwordx4 v172, s[98:99]
	s_mov_b32 m0, s91
	s_nop 0
	s_add_u32 s98, vcc_lo, s46
	s_addc_u32 s99, vcc_hi, s47
	global_load_lds_dwordx4 v172, s[98:99]
	s_waitcnt vmcnt(8)
	s_waitcnt lgkmcnt(0)
	s_barrier
	s_setprio 1
	s_waitcnt lgkmcnt(0)
	v_mfma_i32_16x16x64_i8 v[48:51], v[128:131], v[160:163], v[48:51]
	v_mfma_i32_16x16x64_i8 v[48:51], v[132:135], v[164:167], v[48:51]
	v_mfma_i32_16x16x64_i8 v[0:3], v[136:139], v[160:163], v[0:3]
	v_mfma_i32_16x16x64_i8 v[0:3], v[140:143], v[164:167], v[0:3]
	v_mfma_i32_16x16x64_i8 v[52:55], v[128:131], v[168:171], v[52:55]
	v_mfma_i32_16x16x64_i8 v[52:55], v[132:135], v[192:195], v[52:55]
	v_mfma_i32_16x16x64_i8 v[4:7], v[136:139], v[168:171], v[4:7]
	v_mfma_i32_16x16x64_i8 v[4:7], v[140:143], v[192:195], v[4:7]
	v_mfma_i32_16x16x64_i8 v[56:59], v[128:131], v[196:199], v[56:59]
	v_mfma_i32_16x16x64_i8 v[56:59], v[132:135], v[200:203], v[56:59]
	v_mfma_i32_16x16x64_i8 v[8:11], v[136:139], v[196:199], v[8:11]
	v_mfma_i32_16x16x64_i8 v[8:11], v[140:143], v[200:203], v[8:11]
	v_mfma_i32_16x16x64_i8 v[64:67], v[128:131], v[204:207], v[64:67]
	v_mfma_i32_16x16x64_i8 v[64:67], v[132:135], v[208:211], v[64:67]
	v_mfma_i32_16x16x64_i8 v[12:15], v[136:139], v[204:207], v[12:15]
	v_mfma_i32_16x16x64_i8 v[12:15], v[140:143], v[208:211], v[12:15]
	s_setprio 0
	s_setprio 1
	v_mfma_i32_16x16x64_i8 v[108:111], v[144:147], v[160:163], v[108:111]
	v_mfma_i32_16x16x64_i8 v[108:111], v[148:151], v[164:167], v[108:111]
	v_mfma_i32_16x16x64_i8 v[44:47], v[152:155], v[160:163], v[44:47]
	v_mfma_i32_16x16x64_i8 v[44:47], v[156:159], v[164:167], v[44:47]
	v_mfma_i32_16x16x64_i8 v[104:107], v[144:147], v[168:171], v[104:107]
	v_mfma_i32_16x16x64_i8 v[104:107], v[148:151], v[192:195], v[104:107]
	v_mfma_i32_16x16x64_i8 v[40:43], v[152:155], v[168:171], v[40:43]
	v_mfma_i32_16x16x64_i8 v[40:43], v[156:159], v[192:195], v[40:43]
	v_mfma_i32_16x16x64_i8 v[100:103], v[144:147], v[196:199], v[100:103]
	v_mfma_i32_16x16x64_i8 v[100:103], v[148:151], v[200:203], v[100:103]
	v_mfma_i32_16x16x64_i8 v[32:35], v[152:155], v[196:199], v[32:35]
	v_mfma_i32_16x16x64_i8 v[32:35], v[156:159], v[200:203], v[32:35]
	s_setprio 2
	s_barrier
	v_mfma_i32_16x16x64_i8 v[76:79], v[144:147], v[204:207], v[76:79]
	s_add_i32 s8, s8, 2
	s_add_u32 s75, s75, 0x100
	s_addc_u32 s78, s78, 0
	v_mfma_i32_16x16x64_i8 v[76:79], v[148:151], v[208:211], v[76:79]
	s_add_u32 s6, s6, 0x100
	s_addc_u32 s7, s7, 0
	v_mfma_i32_16x16x64_i8 v[36:39], v[152:155], v[204:207], v[36:39]
	v_mfma_i32_16x16x64_i8 v[36:39], v[156:159], v[208:211], v[36:39]
	s_setprio 0
	s_cmp_gt_u32 s8, 29
	s_cbranch_scc0 .LBB0_800
	s_and_b64 vcc, exec, s[54:55]
	s_cbranch_vccz .LBB0_803
	s_barrier

.LBB0_1034:
	ds_read_b128 v[138:141], v151
	ds_read_b128 v[142:145], v151 offset:1024
	ds_read_b128 v[146:149], v151 offset:2048
	ds_read_b128 v[154:157], v151 offset:3072
	ds_read_b128 v[158:161], v152
	ds_read_b128 v[162:165], v152 offset:1024
	ds_read_b128 v[166:169], v152 offset:2048
	ds_read_b128 v[170:173], v152 offset:3072
	s_add_u32 s47, s44, 0xffd50080
	s_addc_u32 s64, s45, -1
	s_cmpk_eq_i32 s46, 0xa8
	s_cselect_b32 s65, s5, s64
	s_cselect_b32 s64, s4, s47
	s_cselect_b32 s67, s43, s63
	s_cselect_b32 s66, s42, s62
	s_add_i32 m0, s25, 0xc000
	ds_read_b128 v[174:177], v153
	ds_read_b128 v[178:181], v153 offset:1024
	ds_read_b128 v[182:185], v153 offset:2048
	ds_read_b128 v[186:189], v153 offset:3072
	ds_read_b128 v[190:193], v153 offset:4096
	ds_read_b128 v[194:197], v153 offset:5120
	ds_read_b128 v[198:201], v153 offset:6144
	ds_read_b128 v[202:205], v153 offset:7168
	global_load_lds_dwordx4 v132, s[44:45]
	s_add_i32 m0, s25, 0xe000
	s_nop 0
	s_add_u32 s98, s44, s0
	s_addc_u32 s99, s45, s1
	global_load_lds_dwordx4 v132, s[98:99]
	s_waitcnt vmcnt(8)
	s_waitcnt lgkmcnt(0)
	s_barrier
	s_setprio 1
	s_waitcnt lgkmcnt(0)
	v_mfma_f32_16x16x32_bf16 v[124:127], v[138:141], v[174:177], v[124:127]
	v_mfma_f32_16x16x32_bf16 v[124:127], v[142:145], v[178:181], v[124:127]
	v_mfma_f32_16x16x32_bf16 v[120:123], v[146:149], v[174:177], v[120:123]
	v_mfma_f32_16x16x32_bf16 v[120:123], v[154:157], v[178:181], v[120:123]
	v_mfma_f32_16x16x32_bf16 v[116:119], v[138:141], v[182:185], v[116:119]
	v_mfma_f32_16x16x32_bf16 v[116:119], v[142:145], v[186:189], v[116:119]
	v_mfma_f32_16x16x32_bf16 v[112:115], v[146:149], v[182:185], v[112:115]
	v_mfma_f32_16x16x32_bf16 v[112:115], v[154:157], v[186:189], v[112:115]
	v_mfma_f32_16x16x32_bf16 v[108:111], v[138:141], v[190:193], v[108:111]
	v_mfma_f32_16x16x32_bf16 v[108:111], v[142:145], v[194:197], v[108:111]
	v_mfma_f32_16x16x32_bf16 v[104:107], v[146:149], v[190:193], v[104:107]
	v_mfma_f32_16x16x32_bf16 v[104:107], v[154:157], v[194:197], v[104:107]
	v_mfma_f32_16x16x32_bf16 v[100:103], v[138:141], v[198:201], v[100:103]
	v_mfma_f32_16x16x32_bf16 v[100:103], v[142:145], v[202:205], v[100:103]
	v_mfma_f32_16x16x32_bf16 v[96:99], v[146:149], v[198:201], v[96:99]
	v_mfma_f32_16x16x32_bf16 v[96:99], v[154:157], v[202:205], v[96:99]
	s_setprio 0
	s_setprio 1
	v_mfma_f32_16x16x32_bf16 v[92:95], v[158:161], v[174:177], v[92:95]
	v_mfma_f32_16x16x32_bf16 v[92:95], v[162:165], v[178:181], v[92:95]
	v_mfma_f32_16x16x32_bf16 v[88:91], v[166:169], v[174:177], v[88:91]
	v_mfma_f32_16x16x32_bf16 v[88:91], v[170:173], v[178:181], v[88:91]
	v_mfma_f32_16x16x32_bf16 v[84:87], v[158:161], v[182:185], v[84:87]
	v_mfma_f32_16x16x32_bf16 v[84:87], v[162:165], v[186:189], v[84:87]
	v_mfma_f32_16x16x32_bf16 v[80:83], v[166:169], v[182:185], v[80:83]
	v_mfma_f32_16x16x32_bf16 v[80:83], v[170:173], v[186:189], v[80:83]
	v_mfma_f32_16x16x32_bf16 v[76:79], v[158:161], v[190:193], v[76:79]
	v_mfma_f32_16x16x32_bf16 v[76:79], v[162:165], v[194:197], v[76:79]
	v_mfma_f32_16x16x32_bf16 v[72:75], v[166:169], v[190:193], v[72:75]
	v_mfma_f32_16x16x32_bf16 v[72:75], v[170:173], v[194:197], v[72:75]
	s_setprio 2
	s_barrier
	v_mfma_f32_16x16x32_bf16 v[68:71], v[158:161], v[198:201], v[68:71]
	ds_read_b128 v[174:177], v153 offset:16384
	ds_read_b128 v[178:181], v153 offset:17408
	v_mfma_f32_16x16x32_bf16 v[68:71], v[162:165], v[202:205], v[68:71]
	ds_read_b128 v[182:185], v153 offset:18432
	ds_read_b128 v[186:189], v153 offset:19456
	v_mfma_f32_16x16x32_bf16 v[64:67], v[166:169], v[198:201], v[64:67]
	ds_read_b128 v[190:193], v153 offset:20480
	ds_read_b128 v[194:197], v153 offset:21504
	v_mfma_f32_16x16x32_bf16 v[64:67], v[170:173], v[202:205], v[64:67]
	s_setprio 0
	s_add_i32 s47, s56, s24
	s_mov_b32 m0, s47
	ds_read_b128 v[198:201], v153 offset:22528
	ds_read_b128 v[202:205], v153 offset:23552
	global_load_lds_dwordx4 v130, s[66:67]
	s_add_i32 m0, s47, 0x2000
	s_add_i32 s47, s57, s24
	s_add_u32 s98, s66, s0
	s_addc_u32 s99, s67, s1
	global_load_lds_dwordx4 v130, s[98:99]
	s_mov_b32 m0, s47
	s_nop 0
	s_add_u32 s98, s66, s6
	s_addc_u32 s99, s67, s7
	global_load_lds_dwordx4 v130, s[98:99]
	s_add_i32 m0, s47, 0x2000
	s_nop 0
	s_add_u32 s98, s66, s8
	s_addc_u32 s99, s67, s9
	global_load_lds_dwordx4 v130, s[98:99]
	s_mov_b64 s[100:101], s[64:65]
	s_mov_b32 m0, s25
	s_nop 0
	global_load_lds_dwordx4 v128, s[64:65]
	s_mov_b32 m0, s33
	s_nop 0
	s_add_u32 s98, s64, s0
	s_addc_u32 s99, s65, s1
	global_load_lds_dwordx4 v128, s[98:99]
	s_waitcnt vmcnt(8)
	s_waitcnt lgkmcnt(0)
	s_barrier
	s_setprio 1
	s_waitcnt lgkmcnt(0)
	v_mfma_f32_16x16x32_bf16 v[60:63], v[138:141], v[174:177], v[60:63]
	v_mfma_f32_16x16x32_bf16 v[60:63], v[142:145], v[178:181], v[60:63]
	v_mfma_f32_16x16x32_bf16 v[56:59], v[146:149], v[174:177], v[56:59]
	v_mfma_f32_16x16x32_bf16 v[56:59], v[154:157], v[178:181], v[56:59]
	v_mfma_f32_16x16x32_bf16 v[52:55], v[138:141], v[182:185], v[52:55]
	v_mfma_f32_16x16x32_bf16 v[52:55], v[142:145], v[186:189], v[52:55]
	v_mfma_f32_16x16x32_bf16 v[48:51], v[146:149], v[182:185], v[48:51]
	v_mfma_f32_16x16x32_bf16 v[48:51], v[154:157], v[186:189], v[48:51]
	v_mfma_f32_16x16x32_bf16 v[44:47], v[138:141], v[190:193], v[44:47]
	v_mfma_f32_16x16x32_bf16 v[44:47], v[142:145], v[194:197], v[44:47]
	v_mfma_f32_16x16x32_bf16 v[40:43], v[146:149], v[190:193], v[40:43]
	v_mfma_f32_16x16x32_bf16 v[40:43], v[154:157], v[194:197], v[40:43]
	v_mfma_f32_16x16x32_bf16 v[36:39], v[138:141], v[198:201], v[36:39]
	v_mfma_f32_16x16x32_bf16 v[36:39], v[142:145], v[202:205], v[36:39]
	v_mfma_f32_16x16x32_bf16 v[32:35], v[146:149], v[198:201], v[32:35]
	v_mfma_f32_16x16x32_bf16 v[32:35], v[154:157], v[202:205], v[32:35]
	s_setprio 0
	s_setprio 1
	v_mfma_f32_16x16x32_bf16 v[28:31], v[158:161], v[174:177], v[28:31]
	v_mfma_f32_16x16x32_bf16 v[28:31], v[162:165], v[178:181], v[28:31]
	v_mfma_f32_16x16x32_bf16 v[24:27], v[166:169], v[174:177], v[24:27]
	v_mfma_f32_16x16x32_bf16 v[24:27], v[170:173], v[178:181], v[24:27]
	v_mfma_f32_16x16x32_bf16 v[20:23], v[158:161], v[182:185], v[20:23]
	v_mfma_f32_16x16x32_bf16 v[20:23], v[162:165], v[186:189], v[20:23]
	v_mfma_f32_16x16x32_bf16 v[16:19], v[166:169], v[182:185], v[16:19]
	v_mfma_f32_16x16x32_bf16 v[16:19], v[170:173], v[186:189], v[16:19]
	v_mfma_f32_16x16x32_bf16 v[12:15], v[158:161], v[190:193], v[12:15]
	v_mfma_f32_16x16x32_bf16 v[12:15], v[162:165], v[194:197], v[12:15]
	v_mfma_f32_16x16x32_bf16 v[8:11], v[166:169], v[190:193], v[8:11]
	v_mfma_f32_16x16x32_bf16 v[8:11], v[170:173], v[194:197], v[8:11]
	s_setprio 2
	s_barrier
	v_mfma_f32_16x16x32_bf16 v[4:7], v[158:161], v[198:201], v[4:7]
	ds_read_b128 v[174:177], v153 offset:32768
	ds_read_b128 v[178:181], v153 offset:33792
	v_mfma_f32_16x16x32_bf16 v[4:7], v[162:165], v[202:205], v[4:7]
	ds_read_b128 v[182:185], v153 offset:34816
	ds_read_b128 v[186:189], v153 offset:35840
	v_mfma_f32_16x16x32_bf16 v[0:3], v[166:169], v[198:201], v[0:3]
	ds_read_b128 v[190:193], v153 offset:36864
	ds_read_b128 v[194:197], v153 offset:37888
	v_mfma_f32_16x16x32_bf16 v[0:3], v[170:173], v[202:205], v[0:3]
	s_setprio 0
	s_add_i32 s47, 0, 0x18000
	s_add_i32 s64, 0, 0x1c000
	v_add_u32_e32 v154, s47, v150
	v_add_u32_e32 v170, s64, v150
	ds_read_b128 v[138:141], v154
	ds_read_b128 v[142:145], v154 offset:1024
	ds_read_b128 v[146:149], v154 offset:2048
	ds_read_b128 v[154:157], v154 offset:3072
	ds_read_b128 v[158:161], v170
	ds_read_b128 v[162:165], v170 offset:1024
	ds_read_b128 v[166:169], v170 offset:2048
	ds_read_b128 v[170:173], v170 offset:3072
	s_mov_b32 m0, s48
	ds_read_b128 v[198:201], v153 offset:38912
	ds_read_b128 v[202:205], v153 offset:39936
	s_add_u32 s98, s100, s6
	s_addc_u32 s99, s101, s7
	global_load_lds_dwordx4 v128, s[98:99]
	s_mov_b32 m0, s49
	s_nop 0
	s_add_u32 s98, s100, s8
	s_addc_u32 s99, s101, s9
	global_load_lds_dwordx4 v128, s[98:99]
	s_waitcnt vmcnt(8)
	s_waitcnt lgkmcnt(0)
	s_barrier
	s_setprio 1
	s_waitcnt lgkmcnt(0)
	v_mfma_f32_16x16x32_bf16 v[124:127], v[138:141], v[174:177], v[124:127]
	v_mfma_f32_16x16x32_bf16 v[124:127], v[142:145], v[178:181], v[124:127]
	v_mfma_f32_16x16x32_bf16 v[120:123], v[146:149], v[174:177], v[120:123]
	v_mfma_f32_16x16x32_bf16 v[120:123], v[154:157], v[178:181], v[120:123]
	v_mfma_f32_16x16x32_bf16 v[116:119], v[138:141], v[182:185], v[116:119]
	v_mfma_f32_16x16x32_bf16 v[116:119], v[142:145], v[186:189], v[116:119]
	v_mfma_f32_16x16x32_bf16 v[112:115], v[146:149], v[182:185], v[112:115]
	v_mfma_f32_16x16x32_bf16 v[112:115], v[154:157], v[186:189], v[112:115]
	v_mfma_f32_16x16x32_bf16 v[108:111], v[138:141], v[190:193], v[108:111]
	v_mfma_f32_16x16x32_bf16 v[108:111], v[142:145], v[194:197], v[108:111]
	v_mfma_f32_16x16x32_bf16 v[104:107], v[146:149], v[190:193], v[104:107]
	v_mfma_f32_16x16x32_bf16 v[104:107], v[154:157], v[194:197], v[104:107]
	v_mfma_f32_16x16x32_bf16 v[100:103], v[138:141], v[198:201], v[100:103]
	v_mfma_f32_16x16x32_bf16 v[100:103], v[142:145], v[202:205], v[100:103]
	v_mfma_f32_16x16x32_bf16 v[96:99], v[146:149], v[198:201], v[96:99]
	v_mfma_f32_16x16x32_bf16 v[96:99], v[154:157], v[202:205], v[96:99]
	s_setprio 0
	s_setprio 1
	v_mfma_f32_16x16x32_bf16 v[92:95], v[158:161], v[174:177], v[92:95]
	v_mfma_f32_16x16x32_bf16 v[92:95], v[162:165], v[178:181], v[92:95]
	v_mfma_f32_16x16x32_bf16 v[88:91], v[166:169], v[174:177], v[88:91]
	v_mfma_f32_16x16x32_bf16 v[88:91], v[170:173], v[178:181], v[88:91]
	v_mfma_f32_16x16x32_bf16 v[84:87], v[158:161], v[182:185], v[84:87]
	v_mfma_f32_16x16x32_bf16 v[84:87], v[162:165], v[186:189], v[84:87]
	v_mfma_f32_16x16x32_bf16 v[80:83], v[166:169], v[182:185], v[80:83]
	v_mfma_f32_16x16x32_bf16 v[80:83], v[170:173], v[186:189], v[80:83]
	v_mfma_f32_16x16x32_bf16 v[76:79], v[158:161], v[190:193], v[76:79]
	v_mfma_f32_16x16x32_bf16 v[76:79], v[162:165], v[194:197], v[76:79]
	v_mfma_f32_16x16x32_bf16 v[72:75], v[166:169], v[190:193], v[72:75]
	v_mfma_f32_16x16x32_bf16 v[72:75], v[170:173], v[194:197], v[72:75]
	s_setprio 2
	s_barrier
	v_mfma_f32_16x16x32_bf16 v[68:71], v[158:161], v[198:201], v[68:71]
	ds_read_b128 v[174:177], v153 offset:49152
	ds_read_b128 v[178:181], v153 offset:50176
	v_mfma_f32_16x16x32_bf16 v[68:71], v[162:165], v[202:205], v[68:71]
	ds_read_b128 v[182:185], v153 offset:51200
	ds_read_b128 v[186:189], v153 offset:52224
	v_mfma_f32_16x16x32_bf16 v[64:67], v[166:169], v[198:201], v[64:67]
	ds_read_b128 v[190:193], v153 offset:53248
	ds_read_b128 v[194:197], v153 offset:54272
	v_mfma_f32_16x16x32_bf16 v[64:67], v[170:173], v[202:205], v[64:67]
	s_setprio 0
	s_add_i32 s47, s47, s24
	s_mov_b32 m0, s47
	ds_read_b128 v[198:201], v153 offset:55296
	ds_read_b128 v[202:205], v153 offset:56320
	s_add_u32 s98, s66, s16
	s_addc_u32 s99, s67, s17
	global_load_lds_dwordx4 v130, s[98:99]
	s_add_i32 m0, s47, 0x2000
	s_add_i32 s47, s64, s24
	s_add_u32 s98, s66, s20
	s_addc_u32 s99, s67, s21
	global_load_lds_dwordx4 v130, s[98:99]
	s_mov_b32 m0, s47
	s_add_u32 s98, s66, s34
	s_addc_u32 s99, s67, s35
	global_load_lds_dwordx4 v130, s[98:99]
	s_add_i32 m0, s47, 0x2000
	s_nop 0
	s_add_u32 s98, s66, s36
	s_addc_u32 s99, s67, s37
	global_load_lds_dwordx4 v130, s[98:99]
	s_mov_b32 m0, s51
	s_nop 0
	s_add_u32 s98, s100, s16
	s_addc_u32 s99, s101, s17
	global_load_lds_dwordx4 v128, s[98:99]
	s_mov_b32 m0, s52
	s_nop 0
	s_add_u32 s98, s100, s20
	s_addc_u32 s99, s101, s21
	global_load_lds_dwordx4 v128, s[98:99]
	s_waitcnt vmcnt(8)
	s_waitcnt lgkmcnt(0)
	s_barrier
	s_setprio 1
	s_waitcnt lgkmcnt(0)
	v_mfma_f32_16x16x32_bf16 v[60:63], v[138:141], v[174:177], v[60:63]
	v_mfma_f32_16x16x32_bf16 v[60:63], v[142:145], v[178:181], v[60:63]
	v_mfma_f32_16x16x32_bf16 v[56:59], v[146:149], v[174:177], v[56:59]
	v_mfma_f32_16x16x32_bf16 v[56:59], v[154:157], v[178:181], v[56:59]
	v_mfma_f32_16x16x32_bf16 v[52:55], v[138:141], v[182:185], v[52:55]
	v_mfma_f32_16x16x32_bf16 v[52:55], v[142:145], v[186:189], v[52:55]
	v_mfma_f32_16x16x32_bf16 v[48:51], v[146:149], v[182:185], v[48:51]
	v_mfma_f32_16x16x32_bf16 v[48:51], v[154:157], v[186:189], v[48:51]
	v_mfma_f32_16x16x32_bf16 v[44:47], v[138:141], v[190:193], v[44:47]
	v_mfma_f32_16x16x32_bf16 v[44:47], v[142:145], v[194:197], v[44:47]
	v_mfma_f32_16x16x32_bf16 v[40:43], v[146:149], v[190:193], v[40:43]
	v_mfma_f32_16x16x32_bf16 v[40:43], v[154:157], v[194:197], v[40:43]
	v_mfma_f32_16x16x32_bf16 v[36:39], v[138:141], v[198:201], v[36:39]
	v_mfma_f32_16x16x32_bf16 v[36:39], v[142:145], v[202:205], v[36:39]
	v_mfma_f32_16x16x32_bf16 v[32:35], v[146:149], v[198:201], v[32:35]
	v_mfma_f32_16x16x32_bf16 v[32:35], v[154:157], v[202:205], v[32:35]
	s_setprio 0
	s_setprio 1
	v_mfma_f32_16x16x32_bf16 v[28:31], v[158:161], v[174:177], v[28:31]
	v_mfma_f32_16x16x32_bf16 v[28:31], v[162:165], v[178:181], v[28:31]
	v_mfma_f32_16x16x32_bf16 v[24:27], v[166:169], v[174:177], v[24:27]
	v_mfma_f32_16x16x32_bf16 v[24:27], v[170:173], v[178:181], v[24:27]
	v_mfma_f32_16x16x32_bf16 v[20:23], v[158:161], v[182:185], v[20:23]
	v_mfma_f32_16x16x32_bf16 v[20:23], v[162:165], v[186:189], v[20:23]
	v_mfma_f32_16x16x32_bf16 v[16:19], v[166:169], v[182:185], v[16:19]
	v_mfma_f32_16x16x32_bf16 v[16:19], v[170:173], v[186:189], v[16:19]
	v_mfma_f32_16x16x32_bf16 v[12:15], v[158:161], v[190:193], v[12:15]
	v_mfma_f32_16x16x32_bf16 v[12:15], v[162:165], v[194:197], v[12:15]
	v_mfma_f32_16x16x32_bf16 v[8:11], v[166:169], v[190:193], v[8:11]
	v_mfma_f32_16x16x32_bf16 v[8:11], v[170:173], v[194:197], v[8:11]
	s_setprio 2
	s_barrier
	v_mfma_f32_16x16x32_bf16 v[4:7], v[158:161], v[198:201], v[4:7]
	s_add_i32 s46, s46, 2
	s_add_u32 s62, s62, 0x100
	s_addc_u32 s63, s63, 0
	v_mfma_f32_16x16x32_bf16 v[4:7], v[162:165], v[202:205], v[4:7]
	s_add_u32 s44, s44, 0x100
	s_addc_u32 s45, s45, 0
	v_mfma_f32_16x16x32_bf16 v[0:3], v[166:169], v[198:201], v[0:3]
	v_mfma_f32_16x16x32_bf16 v[0:3], v[170:173], v[202:205], v[0:3]
	s_setprio 0
	s_cmpk_gt_u32 s46, 0xa9
	s_cbranch_scc0 .LBB0_1034
	s_and_b64 vcc, exec, s[38:39]
	s_cbranch_vccz .LBB0_1037
	s_barrier

.LBB0_1180:
	ds_read_b128 v[112:115], v181
	ds_read_b128 v[116:119], v181 offset:1024
	ds_read_b128 v[128:131], v181 offset:2048
	ds_read_b128 v[142:145], v181 offset:3072
	ds_read_b128 v[146:149], v202
	ds_read_b128 v[150:153], v202 offset:1024
	ds_read_b128 v[154:157], v202 offset:2048
	ds_read_b128 v[168:171], v202 offset:3072
	s_add_u32 s49, s46, 0xfff80080
	s_addc_u32 s70, s47, -1
	s_cmp_eq_u32 s48, 28
	s_cselect_b32 s71, s39, s70
	s_cselect_b32 s70, s66, s49
	s_cselect_b32 s73, s37, s69
	s_cselect_b32 s72, s67, s68
	s_add_i32 m0, s45, 0xc000
	ds_read_b128 v[172:175], v203
	ds_read_b128 v[182:185], v203 offset:1024
	ds_read_b128 v[186:189], v203 offset:2048
	ds_read_b128 v[190:193], v203 offset:3072
	ds_read_b128 v[194:197], v203 offset:4096
	ds_read_b128 v[198:201], v203 offset:5120
	ds_read_b128 v[206:209], v203 offset:6144
	ds_read_b128 v[210:213], v203 offset:7168
	global_load_lds_dwordx4 v162, s[46:47]
	s_add_i32 m0, s45, 0xe000
	s_nop 0
	s_add_u32 s98, s46, s2
	s_addc_u32 s99, s47, s3
	global_load_lds_dwordx4 v162, s[98:99]
	s_waitcnt vmcnt(8)
	s_waitcnt lgkmcnt(0)
	s_barrier
	s_setprio 1
	s_waitcnt lgkmcnt(0)
	v_mfma_i32_16x16x64_i8 v[138:141], v[112:115], v[172:175], v[138:141]
	v_mfma_i32_16x16x64_i8 v[132:135], v[128:131], v[172:175], v[134:137]
	v_mfma_i32_16x16x64_i8 v[124:127], v[112:115], v[186:189], v[124:127]
	v_mfma_i32_16x16x64_i8 v[120:123], v[128:131], v[186:189], v[120:123]
	v_mfma_i32_16x16x64_i8 v[108:111], v[112:115], v[194:197], v[108:111]
	v_mfma_i32_16x16x64_i8 v[104:107], v[128:131], v[194:197], v[104:107]
	v_mfma_i32_16x16x64_i8 v[100:103], v[112:115], v[206:209], v[100:103]
	v_mfma_i32_16x16x64_i8 v[96:99], v[128:131], v[206:209], v[96:99]
	v_mfma_i32_16x16x64_i8 v[138:141], v[116:119], v[182:185], v[138:141]
	v_mfma_i32_16x16x64_i8 v[132:135], v[142:145], v[182:185], v[132:135]
	v_mfma_i32_16x16x64_i8 v[124:127], v[116:119], v[190:193], v[124:127]
	v_mfma_i32_16x16x64_i8 v[120:123], v[142:145], v[190:193], v[120:123]
	v_mfma_i32_16x16x64_i8 v[108:111], v[116:119], v[198:201], v[108:111]
	v_mfma_i32_16x16x64_i8 v[104:107], v[142:145], v[198:201], v[104:107]
	v_mfma_i32_16x16x64_i8 v[100:103], v[116:119], v[210:213], v[100:103]
	v_mfma_i32_16x16x64_i8 v[96:99], v[142:145], v[210:213], v[96:99]
	s_setprio 0
	s_setprio 1
	v_mfma_i32_16x16x64_i8 v[60:63], v[146:149], v[172:175], v[60:63]
	v_mfma_i32_16x16x64_i8 v[60:63], v[150:153], v[182:185], v[60:63]
	v_mfma_i32_16x16x64_i8 v[56:59], v[154:157], v[172:175], v[56:59]
	v_mfma_i32_16x16x64_i8 v[56:59], v[168:171], v[182:185], v[56:59]
	v_mfma_i32_16x16x64_i8 v[52:55], v[146:149], v[186:189], v[52:55]
	v_mfma_i32_16x16x64_i8 v[52:55], v[150:153], v[190:193], v[52:55]
	v_mfma_i32_16x16x64_i8 v[48:51], v[154:157], v[186:189], v[48:51]
	v_mfma_i32_16x16x64_i8 v[48:51], v[168:171], v[190:193], v[48:51]
	v_mfma_i32_16x16x64_i8 v[44:47], v[146:149], v[194:197], v[44:47]
	v_mfma_i32_16x16x64_i8 v[44:47], v[150:153], v[198:201], v[44:47]
	v_mfma_i32_16x16x64_i8 v[40:43], v[154:157], v[194:197], v[40:43]
	v_mfma_i32_16x16x64_i8 v[40:43], v[168:171], v[198:201], v[40:43]
	s_setprio 2
	s_barrier
	v_mfma_i32_16x16x64_i8 v[36:39], v[146:149], v[206:209], v[36:39]
	ds_read_b128 v[172:175], v203 offset:16384
	ds_read_b128 v[182:185], v203 offset:17408
	v_mfma_i32_16x16x64_i8 v[36:39], v[150:153], v[210:213], v[36:39]
	ds_read_b128 v[186:189], v203 offset:18432
	ds_read_b128 v[190:193], v203 offset:19456
	v_mfma_i32_16x16x64_i8 v[32:35], v[154:157], v[206:209], v[32:35]
	ds_read_b128 v[194:197], v203 offset:20480
	ds_read_b128 v[198:201], v203 offset:21504
	v_mfma_i32_16x16x64_i8 v[32:35], v[168:171], v[210:213], v[32:35]
	s_setprio 0
	s_add_i32 s49, s61, s33
	s_mov_b32 m0, s49
	ds_read_b128 v[206:209], v203 offset:22528
	ds_read_b128 v[210:213], v203 offset:23552
	global_load_lds_dwordx4 v160, s[72:73]
	s_add_i32 m0, s49, 0x2000
	s_add_i32 s49, s62, s33
	s_add_u32 s98, s72, s2
	s_addc_u32 s99, s73, s3
	global_load_lds_dwordx4 v160, s[98:99]
	s_mov_b32 m0, s49
	s_mov_b64 s[100:101], s[70:71]
	s_add_u32 s98, s72, s6
	s_addc_u32 s99, s73, s7
	global_load_lds_dwordx4 v160, s[98:99]
	s_add_i32 m0, s49, 0x2000
	s_nop 0
	s_add_u32 s98, s72, s8
	s_addc_u32 s99, s73, s9
	global_load_lds_dwordx4 v160, s[98:99]
	s_mov_b32 m0, s45
	s_nop 0
	global_load_lds_dwordx4 v158, s[70:71]
	s_mov_b32 m0, s50
	s_nop 0
	s_add_u32 s98, s70, s2
	s_addc_u32 s99, s71, s3
	global_load_lds_dwordx4 v158, s[98:99]
	s_waitcnt vmcnt(8)
	s_waitcnt lgkmcnt(0)
	s_barrier
	s_setprio 1
	s_waitcnt lgkmcnt(0)
	v_mfma_i32_16x16x64_i8 v[92:95], v[112:115], v[172:175], v[92:95]
	v_mfma_i32_16x16x64_i8 v[92:95], v[116:119], v[182:185], v[92:95]
	v_mfma_i32_16x16x64_i8 v[88:91], v[128:131], v[172:175], v[88:91]
	v_mfma_i32_16x16x64_i8 v[88:91], v[142:145], v[182:185], v[88:91]
	v_mfma_i32_16x16x64_i8 v[84:87], v[112:115], v[186:189], v[84:87]
	v_mfma_i32_16x16x64_i8 v[84:87], v[116:119], v[190:193], v[84:87]
	v_mfma_i32_16x16x64_i8 v[80:83], v[128:131], v[186:189], v[80:83]
	v_mfma_i32_16x16x64_i8 v[80:83], v[142:145], v[190:193], v[80:83]
	v_mfma_i32_16x16x64_i8 v[76:79], v[112:115], v[194:197], v[76:79]
	v_mfma_i32_16x16x64_i8 v[76:79], v[116:119], v[198:201], v[76:79]
	v_mfma_i32_16x16x64_i8 v[72:75], v[128:131], v[194:197], v[72:75]
	v_mfma_i32_16x16x64_i8 v[72:75], v[142:145], v[198:201], v[72:75]
	v_mfma_i32_16x16x64_i8 v[68:71], v[112:115], v[206:209], v[68:71]
	v_mfma_i32_16x16x64_i8 v[68:71], v[116:119], v[210:213], v[68:71]
	v_mfma_i32_16x16x64_i8 v[64:67], v[128:131], v[206:209], v[64:67]
	v_mfma_i32_16x16x64_i8 v[64:67], v[142:145], v[210:213], v[64:67]
	s_setprio 0
	s_setprio 1
	v_mfma_i32_16x16x64_i8 v[28:31], v[146:149], v[172:175], v[28:31]
	v_mfma_i32_16x16x64_i8 v[28:31], v[150:153], v[182:185], v[28:31]
	v_mfma_i32_16x16x64_i8 v[24:27], v[154:157], v[172:175], v[24:27]
	v_mfma_i32_16x16x64_i8 v[24:27], v[168:171], v[182:185], v[24:27]
	v_mfma_i32_16x16x64_i8 v[20:23], v[146:149], v[186:189], v[20:23]
	v_mfma_i32_16x16x64_i8 v[20:23], v[150:153], v[190:193], v[20:23]
	v_mfma_i32_16x16x64_i8 v[16:19], v[154:157], v[186:189], v[16:19]
	v_mfma_i32_16x16x64_i8 v[16:19], v[168:171], v[190:193], v[16:19]
	v_mfma_i32_16x16x64_i8 v[12:15], v[146:149], v[194:197], v[12:15]
	v_mfma_i32_16x16x64_i8 v[12:15], v[150:153], v[198:201], v[12:15]
	v_mfma_i32_16x16x64_i8 v[8:11], v[154:157], v[194:197], v[8:11]
	v_mfma_i32_16x16x64_i8 v[8:11], v[168:171], v[198:201], v[8:11]
	s_setprio 2
	s_barrier
	v_mfma_i32_16x16x64_i8 v[4:7], v[146:149], v[206:209], v[4:7]
	ds_read_b128 v[172:175], v203 offset:32768
	ds_read_b128 v[182:185], v203 offset:33792
	v_mfma_i32_16x16x64_i8 v[4:7], v[150:153], v[210:213], v[4:7]
	ds_read_b128 v[186:189], v203 offset:34816
	ds_read_b128 v[190:193], v203 offset:35840
	v_mfma_i32_16x16x64_i8 v[0:3], v[154:157], v[206:209], v[0:3]
	ds_read_b128 v[194:197], v203 offset:36864
	ds_read_b128 v[198:201], v203 offset:37888
	v_mfma_i32_16x16x64_i8 v[0:3], v[168:171], v[210:213], v[0:3]
	s_setprio 0
	s_add_i32 s49, 0, 0x18000
	v_add_u32_e32 v136, s49, v179
	s_add_i32 s70, 0, 0x1c000
	ds_read_b128 v[112:115], v136
	ds_read_b128 v[116:119], v136 offset:1024
	ds_read_b128 v[128:131], v136 offset:2048
	ds_read_b128 v[142:145], v136 offset:3072
	v_add_u32_e32 v136, s70, v179
	ds_read_b128 v[146:149], v136
	ds_read_b128 v[150:153], v136 offset:1024
	ds_read_b128 v[154:157], v136 offset:2048
	ds_read_b128 v[168:171], v136 offset:3072
	s_mov_b32 m0, s51
	ds_read_b128 v[206:209], v203 offset:38912
	ds_read_b128 v[210:213], v203 offset:39936
	s_add_u32 s98, s100, s6
	s_addc_u32 s99, s101, s7
	global_load_lds_dwordx4 v158, s[98:99]
	s_mov_b32 m0, s52
	s_nop 0
	s_add_u32 s98, s100, s8
	s_addc_u32 s99, s101, s9
	global_load_lds_dwordx4 v158, s[98:99]
	s_waitcnt vmcnt(8)
	s_waitcnt lgkmcnt(0)
	s_barrier
	s_setprio 1
	s_waitcnt lgkmcnt(0)
	v_mfma_i32_16x16x64_i8 v[136:139], v[112:115], v[172:175], v[138:141]
	v_mfma_i32_16x16x64_i8 v[132:135], v[128:131], v[172:175], v[132:135]
	v_mfma_i32_16x16x64_i8 v[124:127], v[112:115], v[186:189], v[124:127]
	v_mfma_i32_16x16x64_i8 v[120:123], v[128:131], v[186:189], v[120:123]
	v_mfma_i32_16x16x64_i8 v[108:111], v[112:115], v[194:197], v[108:111]
	v_mfma_i32_16x16x64_i8 v[104:107], v[128:131], v[194:197], v[104:107]
	v_mfma_i32_16x16x64_i8 v[100:103], v[112:115], v[206:209], v[100:103]
	v_mfma_i32_16x16x64_i8 v[96:99], v[128:131], v[206:209], v[96:99]
	v_mfma_i32_16x16x64_i8 v[138:141], v[116:119], v[182:185], v[136:139]
	v_mfma_i32_16x16x64_i8 v[134:137], v[142:145], v[182:185], v[132:135]
	v_mfma_i32_16x16x64_i8 v[124:127], v[116:119], v[190:193], v[124:127]
	v_mfma_i32_16x16x64_i8 v[120:123], v[142:145], v[190:193], v[120:123]
	v_mfma_i32_16x16x64_i8 v[108:111], v[116:119], v[198:201], v[108:111]
	v_mfma_i32_16x16x64_i8 v[104:107], v[142:145], v[198:201], v[104:107]
	v_mfma_i32_16x16x64_i8 v[100:103], v[116:119], v[210:213], v[100:103]
	v_mfma_i32_16x16x64_i8 v[96:99], v[142:145], v[210:213], v[96:99]
	s_setprio 0
	s_setprio 1
	v_mfma_i32_16x16x64_i8 v[60:63], v[146:149], v[172:175], v[60:63]
	v_mfma_i32_16x16x64_i8 v[60:63], v[150:153], v[182:185], v[60:63]
	v_mfma_i32_16x16x64_i8 v[56:59], v[154:157], v[172:175], v[56:59]
	v_mfma_i32_16x16x64_i8 v[56:59], v[168:171], v[182:185], v[56:59]
	v_mfma_i32_16x16x64_i8 v[52:55], v[146:149], v[186:189], v[52:55]
	v_mfma_i32_16x16x64_i8 v[52:55], v[150:153], v[190:193], v[52:55]
	v_mfma_i32_16x16x64_i8 v[48:51], v[154:157], v[186:189], v[48:51]
	v_mfma_i32_16x16x64_i8 v[48:51], v[168:171], v[190:193], v[48:51]
	v_mfma_i32_16x16x64_i8 v[44:47], v[146:149], v[194:197], v[44:47]
	v_mfma_i32_16x16x64_i8 v[44:47], v[150:153], v[198:201], v[44:47]
	v_mfma_i32_16x16x64_i8 v[40:43], v[154:157], v[194:197], v[40:43]
	v_mfma_i32_16x16x64_i8 v[40:43], v[168:171], v[198:201], v[40:43]
	s_setprio 2
	s_barrier
	v_mfma_i32_16x16x64_i8 v[36:39], v[146:149], v[206:209], v[36:39]
	ds_read_b128 v[172:175], v203 offset:49152
	ds_read_b128 v[182:185], v203 offset:50176
	v_mfma_i32_16x16x64_i8 v[36:39], v[150:153], v[210:213], v[36:39]
	ds_read_b128 v[186:189], v203 offset:51200
	ds_read_b128 v[190:193], v203 offset:52224
	v_mfma_i32_16x16x64_i8 v[32:35], v[154:157], v[206:209], v[32:35]
	ds_read_b128 v[194:197], v203 offset:53248
	ds_read_b128 v[198:201], v203 offset:54272
	v_mfma_i32_16x16x64_i8 v[32:35], v[168:171], v[210:213], v[32:35]
	s_setprio 0
	s_add_i32 s49, s49, s33
	s_mov_b32 m0, s49
	ds_read_b128 v[206:209], v203 offset:55296
	ds_read_b128 v[210:213], v203 offset:56320
	s_add_u32 s98, s72, s16
	s_addc_u32 s99, s73, s17
	global_load_lds_dwordx4 v160, s[98:99]
	s_add_i32 m0, s49, 0x2000
	s_add_i32 s49, s70, s33
	s_add_u32 s98, s72, s18
	s_addc_u32 s99, s73, s19
	global_load_lds_dwordx4 v160, s[98:99]
	s_mov_b32 m0, s49
	s_nop 0
	s_add_u32 s98, s72, s20
	s_addc_u32 s99, s73, s21
	global_load_lds_dwordx4 v160, s[98:99]
	s_add_i32 m0, s49, 0x2000
	s_nop 0
	s_add_u32 s98, s72, s30
	s_addc_u32 s99, s73, s31
	global_load_lds_dwordx4 v160, s[98:99]
	s_mov_b32 m0, s54
	s_nop 0
	s_add_u32 s98, s100, s16
	s_addc_u32 s99, s101, s17
	global_load_lds_dwordx4 v158, s[98:99]
	s_mov_b32 m0, s55
	s_nop 0
	s_add_u32 s98, s100, s18
	s_addc_u32 s99, s101, s19
	global_load_lds_dwordx4 v158, s[98:99]
	s_waitcnt vmcnt(8)
	s_waitcnt lgkmcnt(0)
	s_barrier
	s_setprio 1
	s_waitcnt lgkmcnt(0)
	v_mfma_i32_16x16x64_i8 v[92:95], v[112:115], v[172:175], v[92:95]
	v_mfma_i32_16x16x64_i8 v[92:95], v[116:119], v[182:185], v[92:95]
	v_mfma_i32_16x16x64_i8 v[88:91], v[128:131], v[172:175], v[88:91]
	v_mfma_i32_16x16x64_i8 v[88:91], v[142:145], v[182:185], v[88:91]
	v_mfma_i32_16x16x64_i8 v[84:87], v[112:115], v[186:189], v[84:87]
	v_mfma_i32_16x16x64_i8 v[84:87], v[116:119], v[190:193], v[84:87]
	v_mfma_i32_16x16x64_i8 v[80:83], v[128:131], v[186:189], v[80:83]
	v_mfma_i32_16x16x64_i8 v[80:83], v[142:145], v[190:193], v[80:83]
	v_mfma_i32_16x16x64_i8 v[76:79], v[112:115], v[194:197], v[76:79]
	v_mfma_i32_16x16x64_i8 v[76:79], v[116:119], v[198:201], v[76:79]
	v_mfma_i32_16x16x64_i8 v[72:75], v[128:131], v[194:197], v[72:75]
	v_mfma_i32_16x16x64_i8 v[72:75], v[142:145], v[198:201], v[72:75]
	v_mfma_i32_16x16x64_i8 v[68:71], v[112:115], v[206:209], v[68:71]
	v_mfma_i32_16x16x64_i8 v[68:71], v[116:119], v[210:213], v[68:71]
	v_mfma_i32_16x16x64_i8 v[64:67], v[128:131], v[206:209], v[64:67]
	v_mfma_i32_16x16x64_i8 v[64:67], v[142:145], v[210:213], v[64:67]
	s_setprio 0
	s_setprio 1
	v_mfma_i32_16x16x64_i8 v[28:31], v[146:149], v[172:175], v[28:31]
	v_mfma_i32_16x16x64_i8 v[28:31], v[150:153], v[182:185], v[28:31]
	v_mfma_i32_16x16x64_i8 v[24:27], v[154:157], v[172:175], v[24:27]
	v_mfma_i32_16x16x64_i8 v[24:27], v[168:171], v[182:185], v[24:27]
	v_mfma_i32_16x16x64_i8 v[20:23], v[146:149], v[186:189], v[20:23]
	v_mfma_i32_16x16x64_i8 v[20:23], v[150:153], v[190:193], v[20:23]
	v_mfma_i32_16x16x64_i8 v[16:19], v[154:157], v[186:189], v[16:19]
	v_mfma_i32_16x16x64_i8 v[16:19], v[168:171], v[190:193], v[16:19]
	v_mfma_i32_16x16x64_i8 v[12:15], v[146:149], v[194:197], v[12:15]
	v_mfma_i32_16x16x64_i8 v[12:15], v[150:153], v[198:201], v[12:15]
	v_mfma_i32_16x16x64_i8 v[8:11], v[154:157], v[194:197], v[8:11]
	v_mfma_i32_16x16x64_i8 v[8:11], v[168:171], v[198:201], v[8:11]
	s_setprio 2
	s_barrier
	v_mfma_i32_16x16x64_i8 v[4:7], v[146:149], v[206:209], v[4:7]
	s_add_i32 s48, s48, 2
	s_add_u32 s68, s68, 0x100
	s_addc_u32 s69, s69, 0
	v_mfma_i32_16x16x64_i8 v[4:7], v[150:153], v[210:213], v[4:7]
	s_add_u32 s46, s46, 0x100
	s_addc_u32 s47, s47, 0
	v_mfma_i32_16x16x64_i8 v[0:3], v[154:157], v[206:209], v[0:3]
	v_mfma_i32_16x16x64_i8 v[0:3], v[168:171], v[210:213], v[0:3]
	s_setprio 0
	s_cmp_gt_u32 s48, 29
	s_cbranch_scc0 .LBB0_1180
	s_and_b64 vcc, exec, s[34:35]
	s_cbranch_vccz .LBB0_1183
	s_barrier
